# same as v060 but WITHOUT the 4/4 DMA rebalance (baseline 2/6 schedule): ablation-free comparison build
# baseline (speedup 1.0000x reference)
; #define PG8_STAGE(bufoff, gbase, voff) do { _Pragma("unroll") for (int _i = 0; _i < 2; ++_i) \
;         __builtin_amdgcn_global_load_lds((const unsigned*)((const char*)(gbase) + (voff)[_i]), (PG8_LAS unsigned*)(lds + (bufoff) + ldsw + _i * 8192), 16, 0, 0); } while (0)
; #define PG8_LDA(dst, b, h) do { _Pragma("unroll") for (int m = 0; m < 4; ++m) _Pragma("unroll") for (int k = 0; k < 2; ++k) dst[m][k] = *(const PG8_LAS bf16x8*)(lds + PG8_SA(b, h) + aoff + m * 2048 + k * 1024); } while (0)
; #define PG8_LDB(dst, b, h) do { _Pragma("unroll") for (int n = 0; n < 2; ++n) _Pragma("unroll") for (int k = 0; k < 2; ++k) dst[n][k] = *(const PG8_LAS bf16x8*)(lds + PG8_SB(b, h) + boff + n * 2048 + k * 1024); } while (0)
; #define PG8_MMA(ai, bj, At, Bt) do { __builtin_amdgcn_s_setprio(1); _Pragma("unroll") for (int m = 0; m < 4; ++m) _Pragma("unroll") for (int n = 0; n < 2; ++n) _Pragma("unroll") for (int k = 0; k < 2; ++k) \
;         acc[ai][bj][m][n] = __builtin_amdgcn_mfma_f32_16x16x32_bf16(Bt[n][k], At[m][k], acc[ai][bj][m][n], 0, 0, 0); __builtin_amdgcn_s_setprio(0); } while (0)
; #define PG8_WAIT_V(n) asm volatile("s_waitcnt vmcnt(" #n ")" ::: "memory")
; #define PG8_BAR __builtin_amdgcn_s_barrier()
; template <class Epi, class Sched, bool ALIGN_EPI = false, bool SP2 = false>
; __device__ __forceinline__ void gemm_phase(PG8_LAS unsigned char* lds, const Gemm g, const Sched& S, const Epi& E) {
;     ...
;         for (int t = 0; t < nt; t += 2) {
;             const bool last = (t == nt - 2);
;             const char* a1 = cA + (size_t)(t + 1) * kstep;
;             const char* a2 = last ? nA : cA + (size_t)(t + 2) * kstep; const char* b2 = last ? nB : cB + (size_t)(t + 2) * kstep;
;             const char* a3 = a2 + kstep; const char* b3 = b2 + kstep;
;             if (last && has_next) S.a_ready(nxt);
;             if constexpr (SP2) {
;             PG8_LDB(B0, 0, 0); PG8_LDB(B1, 0, 1); PG8_SCHED; PG8_LDA(At, 0, 0); PG8_STAGE(PG8_SA(1, 1), a1 + hstep, voffA);
;             PG8_WAIT_V(8); PG8_WAIT_L(0); PG8_BAR; PG8_MMA(0, 0, At, B0); PG8_MMA(0, 1, At, B1); PG8_BAR; PG8_SCHED;
;             PG8_LDA(At, 0, 1); PG8_STAGE(PG8_SB(0, 0), b2, voffB); PG8_STAGE(PG8_SB(0, 1), b2 + hstep, voffB); PG8_STAGE(PG8_SA(0, 0), a2, voffA);
;             PG8_WAIT_V(8); PG8_WAIT_L(0); PG8_BAR; PG8_MMA(1, 0, At, B0); PG8_MMA(1, 1, At, B1); PG8_BAR; PG8_SCHED;
.LBB0_180:
	ds_read_b128 v[130:133], v170
	ds_read_b128 v[134:137], v170 offset:1024
	ds_read_b128 v[178:181], v170 offset:2048
	ds_read_b128 v[182:185], v170 offset:3072
	ds_read_b128 v[186:189], v171
	ds_read_b128 v[190:193], v171 offset:1024
	ds_read_b128 v[194:197], v171 offset:2048
	ds_read_b128 v[200:203], v171 offset:3072
	s_add_u32 s36, s34, 0xfff00080
	s_addc_u32 s37, s35, -1
	s_cmp_eq_u32 s56, 60
	s_cselect_b32 s39, s7, s37
	s_cselect_b32 s38, s25, s36
	s_cselect_b32 s37, s15, s55
	s_cselect_b32 s36, s31, s54
	s_add_i32 m0, s40, 0xc000
	ds_read_b128 v[204:207], v172
	ds_read_b128 v[208:211], v172 offset:1024
	ds_read_b128 v[212:215], v172 offset:2048
	ds_read_b128 v[216:219], v172 offset:3072
	ds_read_b128 v[220:223], v172 offset:4096
	ds_read_b128 v[224:227], v172 offset:5120
	ds_read_b128 v[228:231], v172 offset:6144
	ds_read_b128 v[232:235], v172 offset:7168
	global_load_lds_dwordx4 v148, s[34:35]
	s_add_i32 m0, s40, 0xe000
	s_nop 0
	global_load_lds_dwordx4 v150, s[34:35]
	s_waitcnt vmcnt(8)
	s_waitcnt lgkmcnt(0)
	s_barrier
	v_mfma_f32_16x16x32_bf16 v[126:129], v[130:133], v[204:207], v[126:129]
	v_mfma_f32_16x16x32_bf16 v[122:125], v[178:181], v[204:207], v[122:125]
	v_mfma_f32_16x16x32_bf16 v[110:113], v[130:133], v[212:215], v[110:113]
	v_mfma_f32_16x16x32_bf16 v[106:109], v[178:181], v[212:215], v[106:109]
	v_mfma_f32_16x16x32_bf16 v[94:97], v[130:133], v[220:223], v[94:97]
	v_mfma_f32_16x16x32_bf16 v[90:93], v[178:181], v[220:223], v[90:93]
	v_mfma_f32_16x16x32_bf16 v[78:81], v[130:133], v[228:231], v[78:81]
	v_mfma_f32_16x16x32_bf16 v[74:77], v[178:181], v[228:231], v[74:77]
	v_mfma_f32_16x16x32_bf16 v[126:129], v[134:137], v[208:211], v[126:129]
	v_mfma_f32_16x16x32_bf16 v[122:125], v[182:185], v[208:211], v[122:125]
	v_mfma_f32_16x16x32_bf16 v[110:113], v[134:137], v[216:219], v[110:113]
	v_mfma_f32_16x16x32_bf16 v[106:109], v[182:185], v[216:219], v[106:109]
	v_mfma_f32_16x16x32_bf16 v[94:97], v[134:137], v[224:227], v[94:97]
	v_mfma_f32_16x16x32_bf16 v[90:93], v[182:185], v[224:227], v[90:93]
	v_mfma_f32_16x16x32_bf16 v[78:81], v[134:137], v[232:235], v[78:81]
	v_mfma_f32_16x16x32_bf16 v[74:77], v[182:185], v[232:235], v[74:77]
	v_mfma_f32_16x16x32_bf16 v[118:121], v[186:189], v[204:207], v[118:121]
	v_mfma_f32_16x16x32_bf16 v[114:117], v[194:197], v[204:207], v[114:117]
	v_mfma_f32_16x16x32_bf16 v[102:105], v[186:189], v[212:215], v[102:105]
	v_mfma_f32_16x16x32_bf16 v[98:101], v[194:197], v[212:215], v[98:101]
	v_mfma_f32_16x16x32_bf16 v[86:89], v[186:189], v[220:223], v[86:89]
	v_mfma_f32_16x16x32_bf16 v[82:85], v[194:197], v[220:223], v[82:85]
	v_mfma_f32_16x16x32_bf16 v[70:73], v[186:189], v[228:231], v[70:73]
	v_mfma_f32_16x16x32_bf16 v[66:69], v[194:197], v[228:231], v[66:69]
	v_mfma_f32_16x16x32_bf16 v[118:121], v[190:193], v[208:211], v[118:121]
	v_mfma_f32_16x16x32_bf16 v[114:117], v[200:203], v[208:211], v[114:117]
	v_mfma_f32_16x16x32_bf16 v[102:105], v[190:193], v[216:219], v[102:105]
	v_mfma_f32_16x16x32_bf16 v[98:101], v[200:203], v[216:219], v[98:101]
	v_mfma_f32_16x16x32_bf16 v[86:89], v[190:193], v[224:227], v[86:89]
	v_mfma_f32_16x16x32_bf16 v[82:85], v[200:203], v[224:227], v[82:85]
	v_mfma_f32_16x16x32_bf16 v[70:73], v[190:193], v[232:235], v[70:73]
	v_mfma_f32_16x16x32_bf16 v[66:69], v[200:203], v[232:235], v[66:69]
	s_barrier
	s_add_i32 s57, s49, s33
	v_lshl_add_u64 v[156:157], s[36:37], 0, v[140:141]
	s_mov_b32 m0, s57
	ds_read_b128 v[204:207], v172 offset:16384
	ds_read_b128 v[208:211], v172 offset:17408
	ds_read_b128 v[212:215], v172 offset:18432
	ds_read_b128 v[216:219], v172 offset:19456
	ds_read_b128 v[220:223], v172 offset:20480
	ds_read_b128 v[224:227], v172 offset:21504
	ds_read_b128 v[228:231], v172 offset:22528
	ds_read_b128 v[232:235], v172 offset:23552
	global_load_lds_dwordx4 v140, s[36:37]
	s_add_i32 m0, s57, 0x2000
	s_add_u32 s58, s36, 0x100000
	v_lshl_add_u64 v[236:237], s[36:37], 0, v[144:145]
	s_addc_u32 s59, s37, 0
	s_add_i32 s57, s50, s33
	global_load_lds_dwordx4 v144, s[36:37]
	s_mov_b32 m0, s57
	v_lshl_add_u64 v[240:241], s[38:39], 0, v[142:143]
	global_load_lds_dwordx4 v140, s[58:59]
	s_add_i32 m0, s57, 0x2000
	s_nop 0
	global_load_lds_dwordx4 v144, s[58:59]
	v_lshl_add_u64 v[238:239], s[38:39], 0, v[138:139]
	s_mov_b32 m0, s40
	s_nop 0
	global_load_lds_dwordx4 v138, s[38:39]
	s_mov_b32 m0, s41
	s_nop 0
	global_load_lds_dwordx4 v142, s[38:39]
	s_waitcnt vmcnt(8)
	s_waitcnt lgkmcnt(0)
	s_barrier
	v_mfma_f32_16x16x32_bf16 v[62:65], v[130:133], v[204:207], v[62:65]
	v_mfma_f32_16x16x32_bf16 v[58:61], v[178:181], v[204:207], v[58:61]
	v_mfma_f32_16x16x32_bf16 v[46:49], v[130:133], v[212:215], v[46:49]
	v_mfma_f32_16x16x32_bf16 v[42:45], v[178:181], v[212:215], v[42:45]
	v_mfma_f32_16x16x32_bf16 v[30:33], v[130:133], v[220:223], v[30:33]
	v_mfma_f32_16x16x32_bf16 v[26:29], v[178:181], v[220:223], v[26:29]
	v_mfma_f32_16x16x32_bf16 v[14:17], v[130:133], v[228:231], v[14:17]
	v_mfma_f32_16x16x32_bf16 v[10:13], v[178:181], v[228:231], v[10:13]
	v_mfma_f32_16x16x32_bf16 v[62:65], v[134:137], v[208:211], v[62:65]
	v_mfma_f32_16x16x32_bf16 v[58:61], v[182:185], v[208:211], v[58:61]
	v_mfma_f32_16x16x32_bf16 v[46:49], v[134:137], v[216:219], v[46:49]
	v_mfma_f32_16x16x32_bf16 v[42:45], v[182:185], v[216:219], v[42:45]
	v_mfma_f32_16x16x32_bf16 v[30:33], v[134:137], v[224:227], v[30:33]
	v_mfma_f32_16x16x32_bf16 v[26:29], v[182:185], v[224:227], v[26:29]
	v_mfma_f32_16x16x32_bf16 v[14:17], v[134:137], v[232:235], v[14:17]
	v_mfma_f32_16x16x32_bf16 v[10:13], v[182:185], v[232:235], v[10:13]
	v_mfma_f32_16x16x32_bf16 v[54:57], v[186:189], v[204:207], v[54:57]
	v_mfma_f32_16x16x32_bf16 v[50:53], v[194:197], v[204:207], v[50:53]
	v_mfma_f32_16x16x32_bf16 v[38:41], v[186:189], v[212:215], v[38:41]
	v_mfma_f32_16x16x32_bf16 v[34:37], v[194:197], v[212:215], v[34:37]
	v_mfma_f32_16x16x32_bf16 v[22:25], v[186:189], v[220:223], v[22:25]
	v_mfma_f32_16x16x32_bf16 v[18:21], v[194:197], v[220:223], v[18:21]
	v_mfma_f32_16x16x32_bf16 v[6:9], v[186:189], v[228:231], v[6:9]
	v_mfma_f32_16x16x32_bf16 v[2:5], v[194:197], v[228:231], v[2:5]
	v_mfma_f32_16x16x32_bf16 v[54:57], v[190:193], v[208:211], v[54:57]
	v_mfma_f32_16x16x32_bf16 v[50:53], v[200:203], v[208:211], v[50:53]
	v_mfma_f32_16x16x32_bf16 v[38:41], v[190:193], v[216:219], v[38:41]
	v_mfma_f32_16x16x32_bf16 v[34:37], v[200:203], v[216:219], v[34:37]
	v_mfma_f32_16x16x32_bf16 v[22:25], v[190:193], v[224:227], v[22:25]
	v_mfma_f32_16x16x32_bf16 v[18:21], v[200:203], v[224:227], v[18:21]
	v_mfma_f32_16x16x32_bf16 v[6:9], v[190:193], v[232:235], v[6:9]
	v_mfma_f32_16x16x32_bf16 v[2:5], v[200:203], v[232:235], v[2:5]
	s_barrier
; #define PG8_STAGE(bufoff, gbase, voff) do { _Pragma("unroll") for (int _i = 0; _i < 2; ++_i) \
;         __builtin_amdgcn_global_load_lds((const unsigned*)((const char*)(gbase) + (voff)[_i]), (PG8_LAS unsigned*)(lds + (bufoff) + ldsw + _i * 8192), 16, 0, 0); } while (0)
; #define PG8_LDA(dst, b, h) do { _Pragma("unroll") for (int m = 0; m < 4; ++m) _Pragma("unroll") for (int k = 0; k < 2; ++k) dst[m][k] = *(const PG8_LAS bf16x8*)(lds + PG8_SA(b, h) + aoff + m * 2048 + k * 1024); } while (0)
; #define PG8_LDB(dst, b, h) do { _Pragma("unroll") for (int n = 0; n < 2; ++n) _Pragma("unroll") for (int k = 0; k < 2; ++k) dst[n][k] = *(const PG8_LAS bf16x8*)(lds + PG8_SB(b, h) + boff + n * 2048 + k * 1024); } while (0)
; #define PG8_MMA(ai, bj, At, Bt) do { __builtin_amdgcn_s_setprio(1); _Pragma("unroll") for (int m = 0; m < 4; ++m) _Pragma("unroll") for (int n = 0; n < 2; ++n) _Pragma("unroll") for (int k = 0; k < 2; ++k) \
;         acc[ai][bj][m][n] = __builtin_amdgcn_mfma_f32_16x16x32_bf16(Bt[n][k], At[m][k], acc[ai][bj][m][n], 0, 0, 0); __builtin_amdgcn_s_setprio(0); } while (0)
; #define PG8_WAIT_V(n) asm volatile("s_waitcnt vmcnt(" #n ")" ::: "memory")
; #define PG8_WAIT_L(n) asm volatile("s_waitcnt lgkmcnt(" #n ")" ::: "memory")
; #define PG8_BAR __builtin_amdgcn_s_barrier()
; #define PG8_SCHED __builtin_amdgcn_sched_barrier(0)
; template <class Epi, class Sched, bool ALIGN_EPI = false, bool SP2 = false>
; __device__ __forceinline__ void gemm_phase(PG8_LAS unsigned char* lds, const Gemm g, const Sched& S, const Epi& E) {
;     ...
;             PG8_LDB(B0, 1, 0); PG8_LDB(B1, 1, 1); PG8_SCHED; PG8_LDA(At, 1, 0); PG8_STAGE(PG8_SA(0, 1), a2 + hstep, voffA);
;             PG8_WAIT_V(8); PG8_WAIT_L(0); PG8_BAR; PG8_MMA(0, 0, At, B0); PG8_MMA(0, 1, At, B1); PG8_BAR; PG8_SCHED;
;             PG8_LDA(At, 1, 1); PG8_STAGE(PG8_SB(1, 0), b3, voffB); PG8_STAGE(PG8_SB(1, 1), b3 + hstep, voffB); PG8_STAGE(PG8_SA(1, 0), a3, voffA);
;             PG8_WAIT_V(8); PG8_WAIT_L(0); PG8_BAR; PG8_MMA(1, 0, At, B0); PG8_MMA(1, 1, At, B1); PG8_BAR; PG8_SCHED;
	s_add_i32 s57, 0, 0x18000
	v_add_u32_e32 v146, s57, v159
	s_add_i32 s58, 0, 0x1c000
	ds_read_b128 v[130:133], v146
	ds_read_b128 v[134:137], v146 offset:1024
	ds_read_b128 v[178:181], v146 offset:2048
	ds_read_b128 v[182:185], v146 offset:3072
	v_add_u32_e32 v146, s58, v159
	ds_read_b128 v[186:189], v146
	ds_read_b128 v[190:193], v146 offset:1024
	ds_read_b128 v[194:197], v146 offset:2048
	ds_read_b128 v[200:203], v146 offset:3072
	s_add_u32 s38, s38, 0x100000
	s_addc_u32 s39, s39, 0
	s_mov_b32 m0, s42
	ds_read_b128 v[204:207], v172 offset:32768
	ds_read_b128 v[208:211], v172 offset:33792
	ds_read_b128 v[212:215], v172 offset:34816
	ds_read_b128 v[216:219], v172 offset:35840
	ds_read_b128 v[220:223], v172 offset:36864
	ds_read_b128 v[224:227], v172 offset:37888
	ds_read_b128 v[228:231], v172 offset:38912
	ds_read_b128 v[232:235], v172 offset:39936
	global_load_lds_dwordx4 v138, s[38:39]
	s_mov_b32 m0, s43
	s_nop 0
	global_load_lds_dwordx4 v142, s[38:39]
	s_waitcnt vmcnt(8)
	s_waitcnt lgkmcnt(0)
	s_barrier
	v_mfma_f32_16x16x32_bf16 v[126:129], v[130:133], v[204:207], v[126:129]
	v_mfma_f32_16x16x32_bf16 v[122:125], v[178:181], v[204:207], v[122:125]
	v_mfma_f32_16x16x32_bf16 v[110:113], v[130:133], v[212:215], v[110:113]
	v_mfma_f32_16x16x32_bf16 v[106:109], v[178:181], v[212:215], v[106:109]
	v_mfma_f32_16x16x32_bf16 v[94:97], v[130:133], v[220:223], v[94:97]
	v_mfma_f32_16x16x32_bf16 v[90:93], v[178:181], v[220:223], v[90:93]
	v_mfma_f32_16x16x32_bf16 v[78:81], v[130:133], v[228:231], v[78:81]
	v_mfma_f32_16x16x32_bf16 v[74:77], v[178:181], v[228:231], v[74:77]
	v_mfma_f32_16x16x32_bf16 v[126:129], v[134:137], v[208:211], v[126:129]
	v_mfma_f32_16x16x32_bf16 v[122:125], v[182:185], v[208:211], v[122:125]
	v_mfma_f32_16x16x32_bf16 v[110:113], v[134:137], v[216:219], v[110:113]
	v_mfma_f32_16x16x32_bf16 v[106:109], v[182:185], v[216:219], v[106:109]
	v_mfma_f32_16x16x32_bf16 v[94:97], v[134:137], v[224:227], v[94:97]
	v_mfma_f32_16x16x32_bf16 v[90:93], v[182:185], v[224:227], v[90:93]
	v_mfma_f32_16x16x32_bf16 v[78:81], v[134:137], v[232:235], v[78:81]
	v_mfma_f32_16x16x32_bf16 v[74:77], v[182:185], v[232:235], v[74:77]
	v_mfma_f32_16x16x32_bf16 v[118:121], v[186:189], v[204:207], v[118:121]
	v_mfma_f32_16x16x32_bf16 v[114:117], v[194:197], v[204:207], v[114:117]
	v_mfma_f32_16x16x32_bf16 v[102:105], v[186:189], v[212:215], v[102:105]
	v_mfma_f32_16x16x32_bf16 v[98:101], v[194:197], v[212:215], v[98:101]
	v_mfma_f32_16x16x32_bf16 v[86:89], v[186:189], v[220:223], v[86:89]
	v_mfma_f32_16x16x32_bf16 v[82:85], v[194:197], v[220:223], v[82:85]
	v_mfma_f32_16x16x32_bf16 v[70:73], v[186:189], v[228:231], v[70:73]
	v_mfma_f32_16x16x32_bf16 v[66:69], v[194:197], v[228:231], v[66:69]
	v_mfma_f32_16x16x32_bf16 v[118:121], v[190:193], v[208:211], v[118:121]
	v_mfma_f32_16x16x32_bf16 v[114:117], v[200:203], v[208:211], v[114:117]
	v_mfma_f32_16x16x32_bf16 v[102:105], v[190:193], v[216:219], v[102:105]
	v_mfma_f32_16x16x32_bf16 v[98:101], v[200:203], v[216:219], v[98:101]
	v_mfma_f32_16x16x32_bf16 v[86:89], v[190:193], v[224:227], v[86:89]
	v_mfma_f32_16x16x32_bf16 v[82:85], v[200:203], v[224:227], v[82:85]
	v_mfma_f32_16x16x32_bf16 v[70:73], v[190:193], v[232:235], v[70:73]
	v_mfma_f32_16x16x32_bf16 v[66:69], v[200:203], v[232:235], v[66:69]
	s_barrier
	s_add_i32 s38, s57, s33
	v_lshl_add_u64 v[156:157], v[156:157], 0, s[10:11]
	s_mov_b32 m0, s38
	ds_read_b128 v[204:207], v172 offset:49152
	ds_read_b128 v[208:211], v172 offset:50176
	ds_read_b128 v[212:215], v172 offset:51200
	ds_read_b128 v[216:219], v172 offset:52224
	ds_read_b128 v[220:223], v172 offset:53248
	ds_read_b128 v[224:227], v172 offset:54272
	ds_read_b128 v[228:231], v172 offset:55296
	ds_read_b128 v[232:235], v172 offset:56320
	global_load_lds_dwordx4 v[156:157], off
	s_add_i32 m0, s38, 0x2000
	s_add_u32 s36, s36, 0x100080
	v_lshl_add_u64 v[156:157], v[236:237], 0, s[10:11]
	s_addc_u32 s37, s37, 0
	s_add_i32 s38, s58, s33
	global_load_lds_dwordx4 v[156:157], off
	s_mov_b32 m0, s38
	s_nop 0
	global_load_lds_dwordx4 v140, s[36:37]
	s_add_i32 m0, s38, 0x2000
	s_nop 0
	global_load_lds_dwordx4 v144, s[36:37]
	v_lshl_add_u64 v[156:157], v[238:239], 0, s[10:11]
	s_mov_b32 m0, s45
	s_nop 0
	global_load_lds_dwordx4 v[156:157], off
	v_lshl_add_u64 v[156:157], v[240:241], 0, s[10:11]
	s_mov_b32 m0, s46
	s_nop 0
	global_load_lds_dwordx4 v[156:157], off
	s_waitcnt vmcnt(8)
	s_waitcnt lgkmcnt(0)
	s_barrier
	v_mfma_f32_16x16x32_bf16 v[62:65], v[130:133], v[204:207], v[62:65]
	v_mfma_f32_16x16x32_bf16 v[58:61], v[178:181], v[204:207], v[58:61]
	v_mfma_f32_16x16x32_bf16 v[46:49], v[130:133], v[212:215], v[46:49]
	v_mfma_f32_16x16x32_bf16 v[42:45], v[178:181], v[212:215], v[42:45]
	v_mfma_f32_16x16x32_bf16 v[30:33], v[130:133], v[220:223], v[30:33]
	v_mfma_f32_16x16x32_bf16 v[26:29], v[178:181], v[220:223], v[26:29]
	v_mfma_f32_16x16x32_bf16 v[14:17], v[130:133], v[228:231], v[14:17]
	v_mfma_f32_16x16x32_bf16 v[10:13], v[178:181], v[228:231], v[10:13]
	v_mfma_f32_16x16x32_bf16 v[62:65], v[134:137], v[208:211], v[62:65]
	v_mfma_f32_16x16x32_bf16 v[58:61], v[182:185], v[208:211], v[58:61]
	v_mfma_f32_16x16x32_bf16 v[46:49], v[134:137], v[216:219], v[46:49]
	v_mfma_f32_16x16x32_bf16 v[42:45], v[182:185], v[216:219], v[42:45]
	v_mfma_f32_16x16x32_bf16 v[30:33], v[134:137], v[224:227], v[30:33]
	v_mfma_f32_16x16x32_bf16 v[26:29], v[182:185], v[224:227], v[26:29]
	v_mfma_f32_16x16x32_bf16 v[14:17], v[134:137], v[232:235], v[14:17]
	v_mfma_f32_16x16x32_bf16 v[10:13], v[182:185], v[232:235], v[10:13]
	v_mfma_f32_16x16x32_bf16 v[54:57], v[186:189], v[204:207], v[54:57]
	v_mfma_f32_16x16x32_bf16 v[50:53], v[194:197], v[204:207], v[50:53]
	v_mfma_f32_16x16x32_bf16 v[38:41], v[186:189], v[212:215], v[38:41]
	v_mfma_f32_16x16x32_bf16 v[34:37], v[194:197], v[212:215], v[34:37]
	v_mfma_f32_16x16x32_bf16 v[22:25], v[186:189], v[220:223], v[22:25]
	v_mfma_f32_16x16x32_bf16 v[18:21], v[194:197], v[220:223], v[18:21]
	v_mfma_f32_16x16x32_bf16 v[6:9], v[186:189], v[228:231], v[6:9]
	v_mfma_f32_16x16x32_bf16 v[2:5], v[194:197], v[228:231], v[2:5]
	v_mfma_f32_16x16x32_bf16 v[54:57], v[190:193], v[208:211], v[54:57]
	v_mfma_f32_16x16x32_bf16 v[50:53], v[200:203], v[208:211], v[50:53]
	v_mfma_f32_16x16x32_bf16 v[38:41], v[190:193], v[216:219], v[38:41]
	v_mfma_f32_16x16x32_bf16 v[34:37], v[200:203], v[216:219], v[34:37]
	v_mfma_f32_16x16x32_bf16 v[22:25], v[190:193], v[224:227], v[22:25]
	v_mfma_f32_16x16x32_bf16 v[18:21], v[200:203], v[224:227], v[18:21]
	v_mfma_f32_16x16x32_bf16 v[6:9], v[190:193], v[232:235], v[6:9]
	v_mfma_f32_16x16x32_bf16 v[2:5], v[200:203], v[232:235], v[2:5]
	s_barrier
	s_add_i32 s56, s56, 2
	s_add_u32 s34, s34, 0x100
	s_addc_u32 s35, s35, 0
	s_add_u32 s54, s54, 0x100
	s_addc_u32 s55, s55, 0
	s_cmp_gt_u32 s56, 61
	s_cbranch_scc0 .LBB0_180
	s_and_b64 vcc, exec, s[12:13]
	s_cbranch_vccz .LBB0_183
	s_barrier

; #define PG8_STAGE(bufoff, gbase, voff) do { _Pragma("unroll") for (int _i = 0; _i < 2; ++_i) \
;         __builtin_amdgcn_global_load_lds((const unsigned*)((const char*)(gbase) + (voff)[_i]), (PG8_LAS unsigned*)(lds + (bufoff) + ldsw + _i * 8192), 16, 0, 0); } while (0)
; #define PG8_LDA(dst, b, h) do { _Pragma("unroll") for (int m = 0; m < 4; ++m) _Pragma("unroll") for (int k = 0; k < 2; ++k) dst[m][k] = *(const PG8_LAS bf16x8*)(lds + PG8_SA(b, h) + aoff + m * 2048 + k * 1024); } while (0)
; #define PG8_LDB(dst, b, h) do { _Pragma("unroll") for (int n = 0; n < 2; ++n) _Pragma("unroll") for (int k = 0; k < 2; ++k) dst[n][k] = *(const PG8_LAS bf16x8*)(lds + PG8_SB(b, h) + boff + n * 2048 + k * 1024); } while (0)
; #define PG8_MMA(ai, bj, At, Bt) do { __builtin_amdgcn_s_setprio(1); _Pragma("unroll") for (int m = 0; m < 4; ++m) _Pragma("unroll") for (int n = 0; n < 2; ++n) _Pragma("unroll") for (int k = 0; k < 2; ++k) \
;         acc[ai][bj][m][n] = __builtin_amdgcn_mfma_f32_16x16x32_bf16(Bt[n][k], At[m][k], acc[ai][bj][m][n], 0, 0, 0); __builtin_amdgcn_s_setprio(0); } while (0)
; #define PG8_WAIT_V(n) asm volatile("s_waitcnt vmcnt(" #n ")" ::: "memory")
; #define PG8_BAR __builtin_amdgcn_s_barrier()
; template <class Epi, class Sched, bool ALIGN_EPI = false, bool SP2 = false>
; __device__ __forceinline__ void gemm_phase(PG8_LAS unsigned char* lds, const Gemm g, const Sched& S, const Epi& E) {
;     ...
;         for (int t = 0; t < nt; t += 2) {
;             const bool last = (t == nt - 2);
;             const char* a1 = cA + (size_t)(t + 1) * kstep;
;             const char* a2 = last ? nA : cA + (size_t)(t + 2) * kstep; const char* b2 = last ? nB : cB + (size_t)(t + 2) * kstep;
;             const char* a3 = a2 + kstep; const char* b3 = b2 + kstep;
;             if (last && has_next) S.a_ready(nxt);
;             if constexpr (SP2) {
;             PG8_LDB(B0, 0, 0); PG8_LDB(B1, 0, 1); PG8_SCHED; PG8_LDA(At, 0, 0); PG8_STAGE(PG8_SA(1, 1), a1 + hstep, voffA);
;             PG8_WAIT_V(8); PG8_WAIT_L(0); PG8_BAR; PG8_MMA(0, 0, At, B0); PG8_MMA(0, 1, At, B1); PG8_BAR; PG8_SCHED;
;             PG8_LDA(At, 0, 1); PG8_STAGE(PG8_SB(0, 0), b2, voffB); PG8_STAGE(PG8_SB(0, 1), b2 + hstep, voffB); PG8_STAGE(PG8_SA(0, 0), a2, voffA);
;             PG8_WAIT_V(8); PG8_WAIT_L(0); PG8_BAR; PG8_MMA(1, 0, At, B0); PG8_MMA(1, 1, At, B1); PG8_BAR; PG8_SCHED;
.LBB0_857:
	ds_read_b128 v[130:133], v180
	ds_read_b128 v[134:137], v180 offset:1024
	ds_read_b128 v[138:141], v180 offset:2048
	ds_read_b128 v[142:145], v180 offset:3072
	ds_read_b128 v[146:149], v181
	ds_read_b128 v[166:169], v181 offset:1024
	ds_read_b128 v[170:173], v181 offset:2048
	ds_read_b128 v[174:177], v181 offset:3072
	s_add_u32 s34, s30, 0xfff80080
	s_addc_u32 s35, s31, -1
	s_cmp_eq_u32 s56, 28
	s_cselect_b32 s37, s15, s35
	s_cselect_b32 s36, s50, s34
	s_cselect_b32 s35, s13, s53
	s_cselect_b32 s34, s51, s52
	s_add_i32 m0, s29, 0xc000
	ds_read_b128 v[184:187], v182
	ds_read_b128 v[188:191], v182 offset:1024
	ds_read_b128 v[192:195], v182 offset:2048
	ds_read_b128 v[200:203], v182 offset:3072
	ds_read_b128 v[204:207], v182 offset:4096
	ds_read_b128 v[208:211], v182 offset:5120
	ds_read_b128 v[212:215], v182 offset:6144
	ds_read_b128 v[216:219], v182 offset:7168
	global_load_lds_dwordx4 v158, s[30:31]
	s_add_i32 m0, s29, 0xe000
	s_nop 0
	global_load_lds_dwordx4 v160, s[30:31]
	s_waitcnt vmcnt(8)
	s_waitcnt lgkmcnt(0)
	s_barrier
	v_mfma_f32_16x16x32_bf16 v[126:129], v[130:133], v[184:187], v[126:129]
	v_mfma_f32_16x16x32_bf16 v[122:125], v[138:141], v[184:187], v[122:125]
	v_mfma_f32_16x16x32_bf16 v[110:113], v[130:133], v[192:195], v[110:113]
	v_mfma_f32_16x16x32_bf16 v[106:109], v[138:141], v[192:195], v[106:109]
	v_mfma_f32_16x16x32_bf16 v[94:97], v[130:133], v[204:207], v[94:97]
	v_mfma_f32_16x16x32_bf16 v[90:93], v[138:141], v[204:207], v[90:93]
	v_mfma_f32_16x16x32_bf16 v[78:81], v[130:133], v[212:215], v[78:81]
	v_mfma_f32_16x16x32_bf16 v[74:77], v[138:141], v[212:215], v[74:77]
	v_mfma_f32_16x16x32_bf16 v[126:129], v[134:137], v[188:191], v[126:129]
	v_mfma_f32_16x16x32_bf16 v[122:125], v[142:145], v[188:191], v[122:125]
	v_mfma_f32_16x16x32_bf16 v[110:113], v[134:137], v[200:203], v[110:113]
	v_mfma_f32_16x16x32_bf16 v[106:109], v[142:145], v[200:203], v[106:109]
	v_mfma_f32_16x16x32_bf16 v[94:97], v[134:137], v[208:211], v[94:97]
	v_mfma_f32_16x16x32_bf16 v[90:93], v[142:145], v[208:211], v[90:93]
	v_mfma_f32_16x16x32_bf16 v[78:81], v[134:137], v[216:219], v[78:81]
	v_mfma_f32_16x16x32_bf16 v[74:77], v[142:145], v[216:219], v[74:77]
	v_mfma_f32_16x16x32_bf16 v[118:121], v[146:149], v[184:187], v[118:121]
	v_mfma_f32_16x16x32_bf16 v[114:117], v[170:173], v[184:187], v[114:117]
	v_mfma_f32_16x16x32_bf16 v[102:105], v[146:149], v[192:195], v[102:105]
	v_mfma_f32_16x16x32_bf16 v[98:101], v[170:173], v[192:195], v[98:101]
	v_mfma_f32_16x16x32_bf16 v[86:89], v[146:149], v[204:207], v[86:89]
	v_mfma_f32_16x16x32_bf16 v[82:85], v[170:173], v[204:207], v[82:85]
	v_mfma_f32_16x16x32_bf16 v[70:73], v[146:149], v[212:215], v[70:73]
	v_mfma_f32_16x16x32_bf16 v[66:69], v[170:173], v[212:215], v[66:69]
	v_mfma_f32_16x16x32_bf16 v[118:121], v[166:169], v[188:191], v[118:121]
	v_mfma_f32_16x16x32_bf16 v[114:117], v[174:177], v[188:191], v[114:117]
	v_mfma_f32_16x16x32_bf16 v[102:105], v[166:169], v[200:203], v[102:105]
	v_mfma_f32_16x16x32_bf16 v[98:101], v[174:177], v[200:203], v[98:101]
	v_mfma_f32_16x16x32_bf16 v[86:89], v[166:169], v[208:211], v[86:89]
	v_mfma_f32_16x16x32_bf16 v[82:85], v[174:177], v[208:211], v[82:85]
	v_mfma_f32_16x16x32_bf16 v[70:73], v[166:169], v[216:219], v[70:73]
	v_mfma_f32_16x16x32_bf16 v[66:69], v[174:177], v[216:219], v[66:69]
	s_barrier
	s_add_i32 s57, s46, s38
	v_lshl_add_u64 v[196:197], s[34:35], 0, v[152:153]
	s_mov_b32 m0, s57
	ds_read_b128 v[184:187], v182 offset:16384
	ds_read_b128 v[188:191], v182 offset:17408
	ds_read_b128 v[192:195], v182 offset:18432
	ds_read_b128 v[200:203], v182 offset:19456
	ds_read_b128 v[204:207], v182 offset:20480
	ds_read_b128 v[208:211], v182 offset:21504
	ds_read_b128 v[212:215], v182 offset:22528
	ds_read_b128 v[216:219], v182 offset:23552
	global_load_lds_dwordx4 v152, s[34:35]
	s_add_i32 m0, s57, 0x2000
	s_add_u32 s58, s34, 0x80000
	v_lshl_add_u64 v[220:221], s[34:35], 0, v[156:157]
	s_addc_u32 s59, s35, 0
	s_add_i32 s57, s47, s38
	global_load_lds_dwordx4 v156, s[34:35]
	s_mov_b32 m0, s57
	v_lshl_add_u64 v[224:225], s[36:37], 0, v[154:155]
	global_load_lds_dwordx4 v152, s[58:59]
	s_add_i32 m0, s57, 0x2000
	s_nop 0
	global_load_lds_dwordx4 v156, s[58:59]
	v_lshl_add_u64 v[222:223], s[36:37], 0, v[150:151]
	s_mov_b32 m0, s29
	s_nop 0
	global_load_lds_dwordx4 v150, s[36:37]
	s_mov_b32 m0, s39
	s_nop 0
	global_load_lds_dwordx4 v154, s[36:37]
	s_waitcnt vmcnt(8)
	s_waitcnt lgkmcnt(0)
	s_barrier
	v_mfma_f32_16x16x32_bf16 v[62:65], v[130:133], v[184:187], v[62:65]
	v_mfma_f32_16x16x32_bf16 v[58:61], v[138:141], v[184:187], v[58:61]
	v_mfma_f32_16x16x32_bf16 v[46:49], v[130:133], v[192:195], v[46:49]
	v_mfma_f32_16x16x32_bf16 v[42:45], v[138:141], v[192:195], v[42:45]
	v_mfma_f32_16x16x32_bf16 v[30:33], v[130:133], v[204:207], v[30:33]
	v_mfma_f32_16x16x32_bf16 v[26:29], v[138:141], v[204:207], v[26:29]
	v_mfma_f32_16x16x32_bf16 v[14:17], v[130:133], v[212:215], v[14:17]
	v_mfma_f32_16x16x32_bf16 v[10:13], v[138:141], v[212:215], v[10:13]
	v_mfma_f32_16x16x32_bf16 v[62:65], v[134:137], v[188:191], v[62:65]
	v_mfma_f32_16x16x32_bf16 v[58:61], v[142:145], v[188:191], v[58:61]
	v_mfma_f32_16x16x32_bf16 v[46:49], v[134:137], v[200:203], v[46:49]
	v_mfma_f32_16x16x32_bf16 v[42:45], v[142:145], v[200:203], v[42:45]
	v_mfma_f32_16x16x32_bf16 v[30:33], v[134:137], v[208:211], v[30:33]
	v_mfma_f32_16x16x32_bf16 v[26:29], v[142:145], v[208:211], v[26:29]
	v_mfma_f32_16x16x32_bf16 v[14:17], v[134:137], v[216:219], v[14:17]
	v_mfma_f32_16x16x32_bf16 v[10:13], v[142:145], v[216:219], v[10:13]
	v_mfma_f32_16x16x32_bf16 v[54:57], v[146:149], v[184:187], v[54:57]
	v_mfma_f32_16x16x32_bf16 v[50:53], v[170:173], v[184:187], v[50:53]
	v_mfma_f32_16x16x32_bf16 v[38:41], v[146:149], v[192:195], v[38:41]
	v_mfma_f32_16x16x32_bf16 v[34:37], v[170:173], v[192:195], v[34:37]
	v_mfma_f32_16x16x32_bf16 v[22:25], v[146:149], v[204:207], v[22:25]
	v_mfma_f32_16x16x32_bf16 v[18:21], v[170:173], v[204:207], v[18:21]
	v_mfma_f32_16x16x32_bf16 v[6:9], v[146:149], v[212:215], v[6:9]
	v_mfma_f32_16x16x32_bf16 v[2:5], v[170:173], v[212:215], v[2:5]
	v_mfma_f32_16x16x32_bf16 v[54:57], v[166:169], v[188:191], v[54:57]
	v_mfma_f32_16x16x32_bf16 v[50:53], v[174:177], v[188:191], v[50:53]
	v_mfma_f32_16x16x32_bf16 v[38:41], v[166:169], v[200:203], v[38:41]
	v_mfma_f32_16x16x32_bf16 v[34:37], v[174:177], v[200:203], v[34:37]
	v_mfma_f32_16x16x32_bf16 v[22:25], v[166:169], v[208:211], v[22:25]
	v_mfma_f32_16x16x32_bf16 v[18:21], v[174:177], v[208:211], v[18:21]
	v_mfma_f32_16x16x32_bf16 v[6:9], v[166:169], v[216:219], v[6:9]
	v_mfma_f32_16x16x32_bf16 v[2:5], v[174:177], v[216:219], v[2:5]
	s_barrier
; #define PG8_STAGE(bufoff, gbase, voff) do { _Pragma("unroll") for (int _i = 0; _i < 2; ++_i) \
;         __builtin_amdgcn_global_load_lds((const unsigned*)((const char*)(gbase) + (voff)[_i]), (PG8_LAS unsigned*)(lds + (bufoff) + ldsw + _i * 8192), 16, 0, 0); } while (0)
; #define PG8_LDA(dst, b, h) do { _Pragma("unroll") for (int m = 0; m < 4; ++m) _Pragma("unroll") for (int k = 0; k < 2; ++k) dst[m][k] = *(const PG8_LAS bf16x8*)(lds + PG8_SA(b, h) + aoff + m * 2048 + k * 1024); } while (0)
; #define PG8_LDB(dst, b, h) do { _Pragma("unroll") for (int n = 0; n < 2; ++n) _Pragma("unroll") for (int k = 0; k < 2; ++k) dst[n][k] = *(const PG8_LAS bf16x8*)(lds + PG8_SB(b, h) + boff + n * 2048 + k * 1024); } while (0)
; #define PG8_MMA(ai, bj, At, Bt) do { __builtin_amdgcn_s_setprio(1); _Pragma("unroll") for (int m = 0; m < 4; ++m) _Pragma("unroll") for (int n = 0; n < 2; ++n) _Pragma("unroll") for (int k = 0; k < 2; ++k) \
;         acc[ai][bj][m][n] = __builtin_amdgcn_mfma_f32_16x16x32_bf16(Bt[n][k], At[m][k], acc[ai][bj][m][n], 0, 0, 0); __builtin_amdgcn_s_setprio(0); } while (0)
; #define PG8_WAIT_V(n) asm volatile("s_waitcnt vmcnt(" #n ")" ::: "memory")
; #define PG8_WAIT_L(n) asm volatile("s_waitcnt lgkmcnt(" #n ")" ::: "memory")
; #define PG8_BAR __builtin_amdgcn_s_barrier()
; #define PG8_SCHED __builtin_amdgcn_sched_barrier(0)
; template <class Epi, class Sched, bool ALIGN_EPI = false, bool SP2 = false>
; __device__ __forceinline__ void gemm_phase(PG8_LAS unsigned char* lds, const Gemm g, const Sched& S, const Epi& E) {
;     ...
;             PG8_LDB(B0, 1, 0); PG8_LDB(B1, 1, 1); PG8_SCHED; PG8_LDA(At, 1, 0); PG8_STAGE(PG8_SA(0, 1), a2 + hstep, voffA);
;             PG8_WAIT_V(8); PG8_WAIT_L(0); PG8_BAR; PG8_MMA(0, 0, At, B0); PG8_MMA(0, 1, At, B1); PG8_BAR; PG8_SCHED;
;             PG8_LDA(At, 1, 1); PG8_STAGE(PG8_SB(1, 0), b3, voffB); PG8_STAGE(PG8_SB(1, 1), b3 + hstep, voffB); PG8_STAGE(PG8_SA(1, 0), a3, voffA);
;             PG8_WAIT_V(8); PG8_WAIT_L(0); PG8_BAR; PG8_MMA(1, 0, At, B0); PG8_MMA(1, 1, At, B1); PG8_BAR; PG8_SCHED;
	s_add_i32 s57, 0, 0x18000
	s_add_i32 s58, 0, 0x1c000
	v_add_u32_e32 v142, s57, v178
	v_add_u32_e32 v174, s58, v178
	ds_read_b128 v[130:133], v142
	ds_read_b128 v[134:137], v142 offset:1024
	ds_read_b128 v[138:141], v142 offset:2048
	ds_read_b128 v[142:145], v142 offset:3072
	ds_read_b128 v[146:149], v174
	ds_read_b128 v[166:169], v174 offset:1024
	ds_read_b128 v[170:173], v174 offset:2048
	ds_read_b128 v[174:177], v174 offset:3072
	s_add_u32 s36, s36, 0x80000
	s_addc_u32 s37, s37, 0
	s_mov_b32 m0, s40
	ds_read_b128 v[184:187], v182 offset:32768
	ds_read_b128 v[188:191], v182 offset:33792
	ds_read_b128 v[192:195], v182 offset:34816
	ds_read_b128 v[200:203], v182 offset:35840
	ds_read_b128 v[204:207], v182 offset:36864
	ds_read_b128 v[208:211], v182 offset:37888
	ds_read_b128 v[212:215], v182 offset:38912
	ds_read_b128 v[216:219], v182 offset:39936
	global_load_lds_dwordx4 v150, s[36:37]
	s_mov_b32 m0, s41
	s_nop 0
	global_load_lds_dwordx4 v154, s[36:37]
	s_waitcnt vmcnt(8)
	s_waitcnt lgkmcnt(0)
	s_barrier
	v_mfma_f32_16x16x32_bf16 v[126:129], v[130:133], v[184:187], v[126:129]
	v_mfma_f32_16x16x32_bf16 v[122:125], v[138:141], v[184:187], v[122:125]
	v_mfma_f32_16x16x32_bf16 v[110:113], v[130:133], v[192:195], v[110:113]
	v_mfma_f32_16x16x32_bf16 v[106:109], v[138:141], v[192:195], v[106:109]
	v_mfma_f32_16x16x32_bf16 v[94:97], v[130:133], v[204:207], v[94:97]
	v_mfma_f32_16x16x32_bf16 v[90:93], v[138:141], v[204:207], v[90:93]
	v_mfma_f32_16x16x32_bf16 v[78:81], v[130:133], v[212:215], v[78:81]
	v_mfma_f32_16x16x32_bf16 v[74:77], v[138:141], v[212:215], v[74:77]
	v_mfma_f32_16x16x32_bf16 v[126:129], v[134:137], v[188:191], v[126:129]
	v_mfma_f32_16x16x32_bf16 v[122:125], v[142:145], v[188:191], v[122:125]
	v_mfma_f32_16x16x32_bf16 v[110:113], v[134:137], v[200:203], v[110:113]
	v_mfma_f32_16x16x32_bf16 v[106:109], v[142:145], v[200:203], v[106:109]
	v_mfma_f32_16x16x32_bf16 v[94:97], v[134:137], v[208:211], v[94:97]
	v_mfma_f32_16x16x32_bf16 v[90:93], v[142:145], v[208:211], v[90:93]
	v_mfma_f32_16x16x32_bf16 v[78:81], v[134:137], v[216:219], v[78:81]
	v_mfma_f32_16x16x32_bf16 v[74:77], v[142:145], v[216:219], v[74:77]
	v_mfma_f32_16x16x32_bf16 v[118:121], v[146:149], v[184:187], v[118:121]
	v_mfma_f32_16x16x32_bf16 v[114:117], v[170:173], v[184:187], v[114:117]
	v_mfma_f32_16x16x32_bf16 v[102:105], v[146:149], v[192:195], v[102:105]
	v_mfma_f32_16x16x32_bf16 v[98:101], v[170:173], v[192:195], v[98:101]
	v_mfma_f32_16x16x32_bf16 v[86:89], v[146:149], v[204:207], v[86:89]
	v_mfma_f32_16x16x32_bf16 v[82:85], v[170:173], v[204:207], v[82:85]
	v_mfma_f32_16x16x32_bf16 v[70:73], v[146:149], v[212:215], v[70:73]
	v_mfma_f32_16x16x32_bf16 v[66:69], v[170:173], v[212:215], v[66:69]
	v_mfma_f32_16x16x32_bf16 v[118:121], v[166:169], v[188:191], v[118:121]
	v_mfma_f32_16x16x32_bf16 v[114:117], v[174:177], v[188:191], v[114:117]
	v_mfma_f32_16x16x32_bf16 v[102:105], v[166:169], v[200:203], v[102:105]
	v_mfma_f32_16x16x32_bf16 v[98:101], v[174:177], v[200:203], v[98:101]
	v_mfma_f32_16x16x32_bf16 v[86:89], v[166:169], v[208:211], v[86:89]
	v_mfma_f32_16x16x32_bf16 v[82:85], v[174:177], v[208:211], v[82:85]
	v_mfma_f32_16x16x32_bf16 v[70:73], v[166:169], v[216:219], v[70:73]
	v_mfma_f32_16x16x32_bf16 v[66:69], v[174:177], v[216:219], v[66:69]
	s_barrier
	s_add_i32 s36, s57, s38
	v_lshl_add_u64 v[196:197], v[196:197], 0, s[8:9]
	s_mov_b32 m0, s36
	ds_read_b128 v[184:187], v182 offset:49152
	ds_read_b128 v[188:191], v182 offset:50176
	ds_read_b128 v[192:195], v182 offset:51200
	ds_read_b128 v[200:203], v182 offset:52224
	ds_read_b128 v[204:207], v182 offset:53248
	ds_read_b128 v[208:211], v182 offset:54272
	ds_read_b128 v[212:215], v182 offset:55296
	ds_read_b128 v[216:219], v182 offset:56320
	global_load_lds_dwordx4 v[196:197], off
	s_add_i32 m0, s36, 0x2000
	s_add_u32 s34, s34, 0x80080
	v_lshl_add_u64 v[196:197], v[220:221], 0, s[8:9]
	s_addc_u32 s35, s35, 0
	s_add_i32 s36, s58, s38
	global_load_lds_dwordx4 v[196:197], off
	s_mov_b32 m0, s36
	s_nop 0
	global_load_lds_dwordx4 v152, s[34:35]
	s_add_i32 m0, s36, 0x2000
	s_nop 0
	global_load_lds_dwordx4 v156, s[34:35]
	v_lshl_add_u64 v[196:197], v[222:223], 0, s[8:9]
	s_mov_b32 m0, s43
	s_nop 0
	global_load_lds_dwordx4 v[196:197], off
	v_lshl_add_u64 v[196:197], v[224:225], 0, s[8:9]
	s_mov_b32 m0, s44
	s_nop 0
	global_load_lds_dwordx4 v[196:197], off
	s_waitcnt vmcnt(8)
	s_waitcnt lgkmcnt(0)
	s_barrier
	v_mfma_f32_16x16x32_bf16 v[62:65], v[130:133], v[184:187], v[62:65]
	v_mfma_f32_16x16x32_bf16 v[58:61], v[138:141], v[184:187], v[58:61]
	v_mfma_f32_16x16x32_bf16 v[46:49], v[130:133], v[192:195], v[46:49]
	v_mfma_f32_16x16x32_bf16 v[42:45], v[138:141], v[192:195], v[42:45]
	v_mfma_f32_16x16x32_bf16 v[30:33], v[130:133], v[204:207], v[30:33]
	v_mfma_f32_16x16x32_bf16 v[26:29], v[138:141], v[204:207], v[26:29]
	v_mfma_f32_16x16x32_bf16 v[14:17], v[130:133], v[212:215], v[14:17]
	v_mfma_f32_16x16x32_bf16 v[10:13], v[138:141], v[212:215], v[10:13]
	v_mfma_f32_16x16x32_bf16 v[62:65], v[134:137], v[188:191], v[62:65]
	v_mfma_f32_16x16x32_bf16 v[58:61], v[142:145], v[188:191], v[58:61]
	v_mfma_f32_16x16x32_bf16 v[46:49], v[134:137], v[200:203], v[46:49]
	v_mfma_f32_16x16x32_bf16 v[42:45], v[142:145], v[200:203], v[42:45]
	v_mfma_f32_16x16x32_bf16 v[30:33], v[134:137], v[208:211], v[30:33]
	v_mfma_f32_16x16x32_bf16 v[26:29], v[142:145], v[208:211], v[26:29]
	v_mfma_f32_16x16x32_bf16 v[14:17], v[134:137], v[216:219], v[14:17]
	v_mfma_f32_16x16x32_bf16 v[10:13], v[142:145], v[216:219], v[10:13]
	v_mfma_f32_16x16x32_bf16 v[54:57], v[146:149], v[184:187], v[54:57]
	v_mfma_f32_16x16x32_bf16 v[50:53], v[170:173], v[184:187], v[50:53]
	v_mfma_f32_16x16x32_bf16 v[38:41], v[146:149], v[192:195], v[38:41]
	v_mfma_f32_16x16x32_bf16 v[34:37], v[170:173], v[192:195], v[34:37]
	v_mfma_f32_16x16x32_bf16 v[22:25], v[146:149], v[204:207], v[22:25]
	v_mfma_f32_16x16x32_bf16 v[18:21], v[170:173], v[204:207], v[18:21]
	v_mfma_f32_16x16x32_bf16 v[6:9], v[146:149], v[212:215], v[6:9]
	v_mfma_f32_16x16x32_bf16 v[2:5], v[170:173], v[212:215], v[2:5]
	v_mfma_f32_16x16x32_bf16 v[54:57], v[166:169], v[188:191], v[54:57]
	v_mfma_f32_16x16x32_bf16 v[50:53], v[174:177], v[188:191], v[50:53]
	v_mfma_f32_16x16x32_bf16 v[38:41], v[166:169], v[200:203], v[38:41]
	v_mfma_f32_16x16x32_bf16 v[34:37], v[174:177], v[200:203], v[34:37]
	v_mfma_f32_16x16x32_bf16 v[22:25], v[166:169], v[208:211], v[22:25]
	v_mfma_f32_16x16x32_bf16 v[18:21], v[174:177], v[208:211], v[18:21]
	v_mfma_f32_16x16x32_bf16 v[6:9], v[166:169], v[216:219], v[6:9]
	v_mfma_f32_16x16x32_bf16 v[2:5], v[174:177], v[216:219], v[2:5]
	s_barrier
	s_add_i32 s56, s56, 2
	s_add_u32 s30, s30, 0x100
	s_addc_u32 s31, s31, 0
	s_add_u32 s52, s52, 0x100
	s_addc_u32 s53, s53, 0
	s_cmp_gt_u32 s56, 29
	s_cbranch_scc0 .LBB0_857
	s_and_b64 vcc, exec, s[10:11]
	s_cbranch_vccz .LBB0_860
	s_barrier

; #define PG8_STAGE(bufoff, gbase, voff) do { _Pragma("unroll") for (int _i = 0; _i < 2; ++_i) \
;         __builtin_amdgcn_global_load_lds((const unsigned*)((const char*)(gbase) + (voff)[_i]), (PG8_LAS unsigned*)(lds + (bufoff) + ldsw + _i * 8192), 16, 0, 0); } while (0)
; #define PG8_LDA(dst, b, h) do { _Pragma("unroll") for (int m = 0; m < 4; ++m) _Pragma("unroll") for (int k = 0; k < 2; ++k) dst[m][k] = *(const PG8_LAS bf16x8*)(lds + PG8_SA(b, h) + aoff + m * 2048 + k * 1024); } while (0)
; #define PG8_LDB(dst, b, h) do { _Pragma("unroll") for (int n = 0; n < 2; ++n) _Pragma("unroll") for (int k = 0; k < 2; ++k) dst[n][k] = *(const PG8_LAS bf16x8*)(lds + PG8_SB(b, h) + boff + n * 2048 + k * 1024); } while (0)
; #define PG8_MMA(ai, bj, At, Bt) do { __builtin_amdgcn_s_setprio(1); _Pragma("unroll") for (int m = 0; m < 4; ++m) _Pragma("unroll") for (int n = 0; n < 2; ++n) _Pragma("unroll") for (int k = 0; k < 2; ++k) \
;         acc[ai][bj][m][n] = __builtin_amdgcn_mfma_f32_16x16x32_bf16(Bt[n][k], At[m][k], acc[ai][bj][m][n], 0, 0, 0); __builtin_amdgcn_s_setprio(0); } while (0)
; #define PG8_WAIT_V(n) asm volatile("s_waitcnt vmcnt(" #n ")" ::: "memory")
; #define PG8_BAR __builtin_amdgcn_s_barrier()
; template <class Epi, class Sched, bool ALIGN_EPI = false, bool SP2 = false>
; __device__ __forceinline__ void gemm_phase(PG8_LAS unsigned char* lds, const Gemm g, const Sched& S, const Epi& E) {
;     ...
;         for (int t = 0; t < nt; t += 2) {
;             const bool last = (t == nt - 2);
;             const char* a1 = cA + (size_t)(t + 1) * kstep;
;             const char* a2 = last ? nA : cA + (size_t)(t + 2) * kstep; const char* b2 = last ? nB : cB + (size_t)(t + 2) * kstep;
;             const char* a3 = a2 + kstep; const char* b3 = b2 + kstep;
;             if (last && has_next) S.a_ready(nxt);
;             if constexpr (SP2) {
;             PG8_LDB(B0, 0, 0); PG8_LDB(B1, 0, 1); PG8_SCHED; PG8_LDA(At, 0, 0); PG8_STAGE(PG8_SA(1, 1), a1 + hstep, voffA);
;             PG8_WAIT_V(8); PG8_WAIT_L(0); PG8_BAR; PG8_MMA(0, 0, At, B0); PG8_MMA(0, 1, At, B1); PG8_BAR; PG8_SCHED;
;             PG8_LDA(At, 0, 1); PG8_STAGE(PG8_SB(0, 0), b2, voffB); PG8_STAGE(PG8_SB(0, 1), b2 + hstep, voffB); PG8_STAGE(PG8_SA(0, 0), a2, voffA);
;             PG8_WAIT_V(8); PG8_WAIT_L(0); PG8_BAR; PG8_MMA(1, 0, At, B0); PG8_MMA(1, 1, At, B1); PG8_BAR; PG8_SCHED;
.LBB0_884:
	ds_read_b128 v[130:133], v211
	ds_read_b128 v[134:137], v211 offset:1024
	ds_read_b128 v[138:141], v211 offset:2048
	ds_read_b128 v[142:145], v211 offset:3072
	ds_read_b128 v[146:149], v212
	ds_read_b128 v[150:153], v212 offset:1024
	ds_read_b128 v[154:157], v212 offset:2048
	ds_read_b128 v[158:161], v212 offset:3072
	s_add_u32 s34, s30, 0xfff80080
	s_addc_u32 s35, s31, -1
	s_cmp_eq_u32 s56, 28
	s_cselect_b32 s37, s15, s35
	s_cselect_b32 s36, s50, s34
	s_cselect_b32 s35, s13, s53
	s_cselect_b32 s34, s51, s52
	s_add_i32 m0, s29, 0xc000
	ds_read_b128 v[162:165], v213
	ds_read_b128 v[166:169], v213 offset:1024
	ds_read_b128 v[170:173], v213 offset:2048
	ds_read_b128 v[174:177], v213 offset:3072
	ds_read_b128 v[194:197], v213 offset:4096
	ds_read_b128 v[200:203], v213 offset:5120
	ds_read_b128 v[204:207], v213 offset:6144
	ds_read_b128 v[214:217], v213 offset:7168
	global_load_lds_dwordx4 v186, s[30:31]
	s_add_i32 m0, s29, 0xe000
	s_nop 0
	global_load_lds_dwordx4 v188, s[30:31]
	s_waitcnt vmcnt(8)
	s_waitcnt lgkmcnt(0)
	s_barrier
	v_mfma_f32_16x16x32_bf16 v[126:129], v[130:133], v[162:165], v[126:129]
	v_mfma_f32_16x16x32_bf16 v[122:125], v[138:141], v[162:165], v[122:125]
	v_mfma_f32_16x16x32_bf16 v[110:113], v[130:133], v[170:173], v[110:113]
	v_mfma_f32_16x16x32_bf16 v[106:109], v[138:141], v[170:173], v[106:109]
	v_mfma_f32_16x16x32_bf16 v[94:97], v[130:133], v[194:197], v[94:97]
	v_mfma_f32_16x16x32_bf16 v[90:93], v[138:141], v[194:197], v[90:93]
	v_mfma_f32_16x16x32_bf16 v[78:81], v[130:133], v[204:207], v[78:81]
	v_mfma_f32_16x16x32_bf16 v[74:77], v[138:141], v[204:207], v[74:77]
	v_mfma_f32_16x16x32_bf16 v[126:129], v[134:137], v[166:169], v[126:129]
	v_mfma_f32_16x16x32_bf16 v[122:125], v[142:145], v[166:169], v[122:125]
	v_mfma_f32_16x16x32_bf16 v[110:113], v[134:137], v[174:177], v[110:113]
	v_mfma_f32_16x16x32_bf16 v[106:109], v[142:145], v[174:177], v[106:109]
	v_mfma_f32_16x16x32_bf16 v[94:97], v[134:137], v[200:203], v[94:97]
	v_mfma_f32_16x16x32_bf16 v[90:93], v[142:145], v[200:203], v[90:93]
	v_mfma_f32_16x16x32_bf16 v[78:81], v[134:137], v[214:217], v[78:81]
	v_mfma_f32_16x16x32_bf16 v[74:77], v[142:145], v[214:217], v[74:77]
	v_mfma_f32_16x16x32_bf16 v[118:121], v[146:149], v[162:165], v[118:121]
	v_mfma_f32_16x16x32_bf16 v[114:117], v[154:157], v[162:165], v[114:117]
	v_mfma_f32_16x16x32_bf16 v[102:105], v[146:149], v[170:173], v[102:105]
	v_mfma_f32_16x16x32_bf16 v[98:101], v[154:157], v[170:173], v[98:101]
	v_mfma_f32_16x16x32_bf16 v[86:89], v[146:149], v[194:197], v[86:89]
	v_mfma_f32_16x16x32_bf16 v[82:85], v[154:157], v[194:197], v[82:85]
	v_mfma_f32_16x16x32_bf16 v[70:73], v[146:149], v[204:207], v[70:73]
	v_mfma_f32_16x16x32_bf16 v[66:69], v[154:157], v[204:207], v[66:69]
	v_mfma_f32_16x16x32_bf16 v[118:121], v[150:153], v[166:169], v[118:121]
	v_mfma_f32_16x16x32_bf16 v[114:117], v[158:161], v[166:169], v[114:117]
	v_mfma_f32_16x16x32_bf16 v[102:105], v[150:153], v[174:177], v[102:105]
	v_mfma_f32_16x16x32_bf16 v[98:101], v[158:161], v[174:177], v[98:101]
	v_mfma_f32_16x16x32_bf16 v[86:89], v[150:153], v[200:203], v[86:89]
	v_mfma_f32_16x16x32_bf16 v[82:85], v[158:161], v[200:203], v[82:85]
	v_mfma_f32_16x16x32_bf16 v[70:73], v[150:153], v[214:217], v[70:73]
	v_mfma_f32_16x16x32_bf16 v[66:69], v[158:161], v[214:217], v[66:69]
	s_barrier
	s_add_i32 s57, s46, s38
	v_lshl_add_u64 v[208:209], s[34:35], 0, v[180:181]
	s_mov_b32 m0, s57
	ds_read_b128 v[162:165], v213 offset:16384
	ds_read_b128 v[166:169], v213 offset:17408
	ds_read_b128 v[170:173], v213 offset:18432
	ds_read_b128 v[174:177], v213 offset:19456
	ds_read_b128 v[194:197], v213 offset:20480
	ds_read_b128 v[200:203], v213 offset:21504
	ds_read_b128 v[204:207], v213 offset:22528
	ds_read_b128 v[214:217], v213 offset:23552
	global_load_lds_dwordx4 v180, s[34:35]
	s_add_i32 m0, s57, 0x2000
	s_add_u32 s58, s34, 0x80000
	v_lshl_add_u64 v[218:219], s[34:35], 0, v[184:185]
	s_addc_u32 s59, s35, 0
	s_add_i32 s57, s47, s38
	global_load_lds_dwordx4 v184, s[34:35]
	s_mov_b32 m0, s57
	v_lshl_add_u64 v[222:223], s[36:37], 0, v[182:183]
	global_load_lds_dwordx4 v180, s[58:59]
	s_add_i32 m0, s57, 0x2000
	s_nop 0
	global_load_lds_dwordx4 v184, s[58:59]
	v_lshl_add_u64 v[220:221], s[36:37], 0, v[178:179]
	s_mov_b32 m0, s29
	s_nop 0
	global_load_lds_dwordx4 v178, s[36:37]
	s_mov_b32 m0, s39
	s_nop 0
	global_load_lds_dwordx4 v182, s[36:37]
	s_waitcnt vmcnt(8)
	s_waitcnt lgkmcnt(0)
	s_barrier
	v_mfma_f32_16x16x32_bf16 v[62:65], v[130:133], v[162:165], v[62:65]
	v_mfma_f32_16x16x32_bf16 v[58:61], v[138:141], v[162:165], v[58:61]
	v_mfma_f32_16x16x32_bf16 v[46:49], v[130:133], v[170:173], v[46:49]
	v_mfma_f32_16x16x32_bf16 v[42:45], v[138:141], v[170:173], v[42:45]
	v_mfma_f32_16x16x32_bf16 v[30:33], v[130:133], v[194:197], v[30:33]
	v_mfma_f32_16x16x32_bf16 v[26:29], v[138:141], v[194:197], v[26:29]
	v_mfma_f32_16x16x32_bf16 v[14:17], v[130:133], v[204:207], v[14:17]
	v_mfma_f32_16x16x32_bf16 v[10:13], v[138:141], v[204:207], v[10:13]
	v_mfma_f32_16x16x32_bf16 v[62:65], v[134:137], v[166:169], v[62:65]
	v_mfma_f32_16x16x32_bf16 v[58:61], v[142:145], v[166:169], v[58:61]
	v_mfma_f32_16x16x32_bf16 v[46:49], v[134:137], v[174:177], v[46:49]
	v_mfma_f32_16x16x32_bf16 v[42:45], v[142:145], v[174:177], v[42:45]
	v_mfma_f32_16x16x32_bf16 v[30:33], v[134:137], v[200:203], v[30:33]
	v_mfma_f32_16x16x32_bf16 v[26:29], v[142:145], v[200:203], v[26:29]
	v_mfma_f32_16x16x32_bf16 v[14:17], v[134:137], v[214:217], v[14:17]
	v_mfma_f32_16x16x32_bf16 v[10:13], v[142:145], v[214:217], v[10:13]
	v_mfma_f32_16x16x32_bf16 v[54:57], v[146:149], v[162:165], v[54:57]
	v_mfma_f32_16x16x32_bf16 v[50:53], v[154:157], v[162:165], v[50:53]
	v_mfma_f32_16x16x32_bf16 v[38:41], v[146:149], v[170:173], v[38:41]
	v_mfma_f32_16x16x32_bf16 v[34:37], v[154:157], v[170:173], v[34:37]
	v_mfma_f32_16x16x32_bf16 v[22:25], v[146:149], v[194:197], v[22:25]
	v_mfma_f32_16x16x32_bf16 v[18:21], v[154:157], v[194:197], v[18:21]
	v_mfma_f32_16x16x32_bf16 v[6:9], v[146:149], v[204:207], v[6:9]
	v_mfma_f32_16x16x32_bf16 v[2:5], v[154:157], v[204:207], v[2:5]
	v_mfma_f32_16x16x32_bf16 v[54:57], v[150:153], v[166:169], v[54:57]
	v_mfma_f32_16x16x32_bf16 v[50:53], v[158:161], v[166:169], v[50:53]
	v_mfma_f32_16x16x32_bf16 v[38:41], v[150:153], v[174:177], v[38:41]
	v_mfma_f32_16x16x32_bf16 v[34:37], v[158:161], v[174:177], v[34:37]
	v_mfma_f32_16x16x32_bf16 v[22:25], v[150:153], v[200:203], v[22:25]
	v_mfma_f32_16x16x32_bf16 v[18:21], v[158:161], v[200:203], v[18:21]
	v_mfma_f32_16x16x32_bf16 v[6:9], v[150:153], v[214:217], v[6:9]
	v_mfma_f32_16x16x32_bf16 v[2:5], v[158:161], v[214:217], v[2:5]
	s_barrier
; #define PG8_STAGE(bufoff, gbase, voff) do { _Pragma("unroll") for (int _i = 0; _i < 2; ++_i) \
;         __builtin_amdgcn_global_load_lds((const unsigned*)((const char*)(gbase) + (voff)[_i]), (PG8_LAS unsigned*)(lds + (bufoff) + ldsw + _i * 8192), 16, 0, 0); } while (0)
; #define PG8_LDA(dst, b, h) do { _Pragma("unroll") for (int m = 0; m < 4; ++m) _Pragma("unroll") for (int k = 0; k < 2; ++k) dst[m][k] = *(const PG8_LAS bf16x8*)(lds + PG8_SA(b, h) + aoff + m * 2048 + k * 1024); } while (0)
; #define PG8_LDB(dst, b, h) do { _Pragma("unroll") for (int n = 0; n < 2; ++n) _Pragma("unroll") for (int k = 0; k < 2; ++k) dst[n][k] = *(const PG8_LAS bf16x8*)(lds + PG8_SB(b, h) + boff + n * 2048 + k * 1024); } while (0)
; #define PG8_MMA(ai, bj, At, Bt) do { __builtin_amdgcn_s_setprio(1); _Pragma("unroll") for (int m = 0; m < 4; ++m) _Pragma("unroll") for (int n = 0; n < 2; ++n) _Pragma("unroll") for (int k = 0; k < 2; ++k) \
;         acc[ai][bj][m][n] = __builtin_amdgcn_mfma_f32_16x16x32_bf16(Bt[n][k], At[m][k], acc[ai][bj][m][n], 0, 0, 0); __builtin_amdgcn_s_setprio(0); } while (0)
; #define PG8_WAIT_V(n) asm volatile("s_waitcnt vmcnt(" #n ")" ::: "memory")
; #define PG8_WAIT_L(n) asm volatile("s_waitcnt lgkmcnt(" #n ")" ::: "memory")
; #define PG8_BAR __builtin_amdgcn_s_barrier()
; #define PG8_SCHED __builtin_amdgcn_sched_barrier(0)
; template <class Epi, class Sched, bool ALIGN_EPI = false, bool SP2 = false>
; __device__ __forceinline__ void gemm_phase(PG8_LAS unsigned char* lds, const Gemm g, const Sched& S, const Epi& E) {
;     ...
;             PG8_LDB(B0, 1, 0); PG8_LDB(B1, 1, 1); PG8_SCHED; PG8_LDA(At, 1, 0); PG8_STAGE(PG8_SA(0, 1), a2 + hstep, voffA);
;             PG8_WAIT_V(8); PG8_WAIT_L(0); PG8_BAR; PG8_MMA(0, 0, At, B0); PG8_MMA(0, 1, At, B1); PG8_BAR; PG8_SCHED;
;             PG8_LDA(At, 1, 1); PG8_STAGE(PG8_SB(1, 0), b3, voffB); PG8_STAGE(PG8_SB(1, 1), b3 + hstep, voffB); PG8_STAGE(PG8_SA(1, 0), a3, voffA);
;             PG8_WAIT_V(8); PG8_WAIT_L(0); PG8_BAR; PG8_MMA(1, 0, At, B0); PG8_MMA(1, 1, At, B1); PG8_BAR; PG8_SCHED;
	s_add_i32 s57, 0, 0x18000
	s_add_i32 s58, 0, 0x1c000
	v_add_u32_e32 v142, s57, v199
	v_add_u32_e32 v158, s58, v199
	ds_read_b128 v[130:133], v142
	ds_read_b128 v[134:137], v142 offset:1024
	ds_read_b128 v[138:141], v142 offset:2048
	ds_read_b128 v[142:145], v142 offset:3072
	ds_read_b128 v[146:149], v158
	ds_read_b128 v[150:153], v158 offset:1024
	ds_read_b128 v[154:157], v158 offset:2048
	ds_read_b128 v[158:161], v158 offset:3072
	s_add_u32 s36, s36, 0x80000
	s_addc_u32 s37, s37, 0
	s_mov_b32 m0, s40
	ds_read_b128 v[162:165], v213 offset:32768
	ds_read_b128 v[166:169], v213 offset:33792
	ds_read_b128 v[170:173], v213 offset:34816
	ds_read_b128 v[174:177], v213 offset:35840
	ds_read_b128 v[194:197], v213 offset:36864
	ds_read_b128 v[200:203], v213 offset:37888
	ds_read_b128 v[204:207], v213 offset:38912
	ds_read_b128 v[214:217], v213 offset:39936
	global_load_lds_dwordx4 v178, s[36:37]
	s_mov_b32 m0, s41
	s_nop 0
	global_load_lds_dwordx4 v182, s[36:37]
	s_waitcnt vmcnt(8)
	s_waitcnt lgkmcnt(0)
	s_barrier
	v_mfma_f32_16x16x32_bf16 v[126:129], v[130:133], v[162:165], v[126:129]
	v_mfma_f32_16x16x32_bf16 v[122:125], v[138:141], v[162:165], v[122:125]
	v_mfma_f32_16x16x32_bf16 v[110:113], v[130:133], v[170:173], v[110:113]
	v_mfma_f32_16x16x32_bf16 v[106:109], v[138:141], v[170:173], v[106:109]
	v_mfma_f32_16x16x32_bf16 v[94:97], v[130:133], v[194:197], v[94:97]
	v_mfma_f32_16x16x32_bf16 v[90:93], v[138:141], v[194:197], v[90:93]
	v_mfma_f32_16x16x32_bf16 v[78:81], v[130:133], v[204:207], v[78:81]
	v_mfma_f32_16x16x32_bf16 v[74:77], v[138:141], v[204:207], v[74:77]
	v_mfma_f32_16x16x32_bf16 v[126:129], v[134:137], v[166:169], v[126:129]
	v_mfma_f32_16x16x32_bf16 v[122:125], v[142:145], v[166:169], v[122:125]
	v_mfma_f32_16x16x32_bf16 v[110:113], v[134:137], v[174:177], v[110:113]
	v_mfma_f32_16x16x32_bf16 v[106:109], v[142:145], v[174:177], v[106:109]
	v_mfma_f32_16x16x32_bf16 v[94:97], v[134:137], v[200:203], v[94:97]
	v_mfma_f32_16x16x32_bf16 v[90:93], v[142:145], v[200:203], v[90:93]
	v_mfma_f32_16x16x32_bf16 v[78:81], v[134:137], v[214:217], v[78:81]
	v_mfma_f32_16x16x32_bf16 v[74:77], v[142:145], v[214:217], v[74:77]
	v_mfma_f32_16x16x32_bf16 v[118:121], v[146:149], v[162:165], v[118:121]
	v_mfma_f32_16x16x32_bf16 v[114:117], v[154:157], v[162:165], v[114:117]
	v_mfma_f32_16x16x32_bf16 v[102:105], v[146:149], v[170:173], v[102:105]
	v_mfma_f32_16x16x32_bf16 v[98:101], v[154:157], v[170:173], v[98:101]
	v_mfma_f32_16x16x32_bf16 v[86:89], v[146:149], v[194:197], v[86:89]
	v_mfma_f32_16x16x32_bf16 v[82:85], v[154:157], v[194:197], v[82:85]
	v_mfma_f32_16x16x32_bf16 v[70:73], v[146:149], v[204:207], v[70:73]
	v_mfma_f32_16x16x32_bf16 v[66:69], v[154:157], v[204:207], v[66:69]
	v_mfma_f32_16x16x32_bf16 v[118:121], v[150:153], v[166:169], v[118:121]
	v_mfma_f32_16x16x32_bf16 v[114:117], v[158:161], v[166:169], v[114:117]
	v_mfma_f32_16x16x32_bf16 v[102:105], v[150:153], v[174:177], v[102:105]
	v_mfma_f32_16x16x32_bf16 v[98:101], v[158:161], v[174:177], v[98:101]
	v_mfma_f32_16x16x32_bf16 v[86:89], v[150:153], v[200:203], v[86:89]
	v_mfma_f32_16x16x32_bf16 v[82:85], v[158:161], v[200:203], v[82:85]
	v_mfma_f32_16x16x32_bf16 v[70:73], v[150:153], v[214:217], v[70:73]
	v_mfma_f32_16x16x32_bf16 v[66:69], v[158:161], v[214:217], v[66:69]
	s_barrier
	s_add_i32 s36, s57, s38
	v_lshl_add_u64 v[208:209], v[208:209], 0, s[8:9]
	s_mov_b32 m0, s36
	ds_read_b128 v[162:165], v213 offset:49152
	ds_read_b128 v[166:169], v213 offset:50176
	ds_read_b128 v[170:173], v213 offset:51200
	ds_read_b128 v[174:177], v213 offset:52224
	ds_read_b128 v[194:197], v213 offset:53248
	ds_read_b128 v[200:203], v213 offset:54272
	ds_read_b128 v[204:207], v213 offset:55296
	ds_read_b128 v[214:217], v213 offset:56320
	global_load_lds_dwordx4 v[208:209], off
	s_add_i32 m0, s36, 0x2000
	s_add_u32 s34, s34, 0x80080
	v_lshl_add_u64 v[208:209], v[218:219], 0, s[8:9]
	s_addc_u32 s35, s35, 0
	s_add_i32 s36, s58, s38
	global_load_lds_dwordx4 v[208:209], off
	s_mov_b32 m0, s36
	s_nop 0
	global_load_lds_dwordx4 v180, s[34:35]
	s_add_i32 m0, s36, 0x2000
	s_nop 0
	global_load_lds_dwordx4 v184, s[34:35]
	v_lshl_add_u64 v[208:209], v[220:221], 0, s[8:9]
	s_mov_b32 m0, s43
	s_nop 0
	global_load_lds_dwordx4 v[208:209], off
	v_lshl_add_u64 v[208:209], v[222:223], 0, s[8:9]
	s_mov_b32 m0, s44
	s_nop 0
	global_load_lds_dwordx4 v[208:209], off
	s_waitcnt vmcnt(8)
	s_waitcnt lgkmcnt(0)
	s_barrier
	v_mfma_f32_16x16x32_bf16 v[62:65], v[130:133], v[162:165], v[62:65]
	v_mfma_f32_16x16x32_bf16 v[58:61], v[138:141], v[162:165], v[58:61]
	v_mfma_f32_16x16x32_bf16 v[46:49], v[130:133], v[170:173], v[46:49]
	v_mfma_f32_16x16x32_bf16 v[42:45], v[138:141], v[170:173], v[42:45]
	v_mfma_f32_16x16x32_bf16 v[30:33], v[130:133], v[194:197], v[30:33]
	v_mfma_f32_16x16x32_bf16 v[26:29], v[138:141], v[194:197], v[26:29]
	v_mfma_f32_16x16x32_bf16 v[14:17], v[130:133], v[204:207], v[14:17]
	v_mfma_f32_16x16x32_bf16 v[10:13], v[138:141], v[204:207], v[10:13]
	v_mfma_f32_16x16x32_bf16 v[62:65], v[134:137], v[166:169], v[62:65]
	v_mfma_f32_16x16x32_bf16 v[58:61], v[142:145], v[166:169], v[58:61]
	v_mfma_f32_16x16x32_bf16 v[46:49], v[134:137], v[174:177], v[46:49]
	v_mfma_f32_16x16x32_bf16 v[42:45], v[142:145], v[174:177], v[42:45]
	v_mfma_f32_16x16x32_bf16 v[30:33], v[134:137], v[200:203], v[30:33]
	v_mfma_f32_16x16x32_bf16 v[26:29], v[142:145], v[200:203], v[26:29]
	v_mfma_f32_16x16x32_bf16 v[14:17], v[134:137], v[214:217], v[14:17]
	v_mfma_f32_16x16x32_bf16 v[10:13], v[142:145], v[214:217], v[10:13]
	v_mfma_f32_16x16x32_bf16 v[54:57], v[146:149], v[162:165], v[54:57]
	v_mfma_f32_16x16x32_bf16 v[50:53], v[154:157], v[162:165], v[50:53]
	v_mfma_f32_16x16x32_bf16 v[38:41], v[146:149], v[170:173], v[38:41]
	v_mfma_f32_16x16x32_bf16 v[34:37], v[154:157], v[170:173], v[34:37]
	v_mfma_f32_16x16x32_bf16 v[22:25], v[146:149], v[194:197], v[22:25]
	v_mfma_f32_16x16x32_bf16 v[18:21], v[154:157], v[194:197], v[18:21]
	v_mfma_f32_16x16x32_bf16 v[6:9], v[146:149], v[204:207], v[6:9]
	v_mfma_f32_16x16x32_bf16 v[2:5], v[154:157], v[204:207], v[2:5]
	v_mfma_f32_16x16x32_bf16 v[54:57], v[150:153], v[166:169], v[54:57]
	v_mfma_f32_16x16x32_bf16 v[50:53], v[158:161], v[166:169], v[50:53]
	v_mfma_f32_16x16x32_bf16 v[38:41], v[150:153], v[174:177], v[38:41]
	v_mfma_f32_16x16x32_bf16 v[34:37], v[158:161], v[174:177], v[34:37]
	v_mfma_f32_16x16x32_bf16 v[22:25], v[150:153], v[200:203], v[22:25]
	v_mfma_f32_16x16x32_bf16 v[18:21], v[158:161], v[200:203], v[18:21]
	v_mfma_f32_16x16x32_bf16 v[6:9], v[150:153], v[214:217], v[6:9]
	v_mfma_f32_16x16x32_bf16 v[2:5], v[158:161], v[214:217], v[2:5]
	s_barrier
	s_add_i32 s56, s56, 2
	s_add_u32 s30, s30, 0x100
	s_addc_u32 s31, s31, 0
	s_add_u32 s52, s52, 0x100
	s_addc_u32 s53, s53, 0
	s_cmp_gt_u32 s56, 29
	s_cbranch_scc0 .LBB0_884
	s_and_b64 vcc, exec, s[10:11]
	s_cbranch_vccz .LBB0_887
	s_barrier

; #define PG8_STAGE(bufoff, gbase, voff) do { _Pragma("unroll") for (int _i = 0; _i < 2; ++_i) \
;         __builtin_amdgcn_global_load_lds((const unsigned*)((const char*)(gbase) + (voff)[_i]), (PG8_LAS unsigned*)(lds + (bufoff) + ldsw + _i * 8192), 16, 0, 0); } while (0)
; #define PG8_LDA(dst, b, h) do { _Pragma("unroll") for (int m = 0; m < 4; ++m) _Pragma("unroll") for (int k = 0; k < 2; ++k) dst[m][k] = *(const PG8_LAS bf16x8*)(lds + PG8_SA(b, h) + aoff + m * 2048 + k * 1024); } while (0)
; #define PG8_LDB(dst, b, h) do { _Pragma("unroll") for (int n = 0; n < 2; ++n) _Pragma("unroll") for (int k = 0; k < 2; ++k) dst[n][k] = *(const PG8_LAS bf16x8*)(lds + PG8_SB(b, h) + boff + n * 2048 + k * 1024); } while (0)
; #define PG8_MMA(ai, bj, At, Bt) do { __builtin_amdgcn_s_setprio(1); _Pragma("unroll") for (int m = 0; m < 4; ++m) _Pragma("unroll") for (int n = 0; n < 2; ++n) _Pragma("unroll") for (int k = 0; k < 2; ++k) \
;         acc[ai][bj][m][n] = __builtin_amdgcn_mfma_f32_16x16x32_bf16(Bt[n][k], At[m][k], acc[ai][bj][m][n], 0, 0, 0); __builtin_amdgcn_s_setprio(0); } while (0)
; #define PG8_WAIT_V(n) asm volatile("s_waitcnt vmcnt(" #n ")" ::: "memory")
; #define PG8_BAR __builtin_amdgcn_s_barrier()
; template <class Epi, class Sched, bool ALIGN_EPI = false, bool SP2 = false>
; __device__ __forceinline__ void gemm_phase(PG8_LAS unsigned char* lds, const Gemm g, const Sched& S, const Epi& E) {
;     ...
;         for (int t = 0; t < nt; t += 2) {
;             const bool last = (t == nt - 2);
;             const char* a1 = cA + (size_t)(t + 1) * kstep;
;             const char* a2 = last ? nA : cA + (size_t)(t + 2) * kstep; const char* b2 = last ? nB : cB + (size_t)(t + 2) * kstep;
;             const char* a3 = a2 + kstep; const char* b3 = b2 + kstep;
;             if (last && has_next) S.a_ready(nxt);
;             if constexpr (SP2) {
;             PG8_LDB(B0, 0, 0); PG8_LDB(B1, 0, 1); PG8_SCHED; PG8_LDA(At, 0, 0); PG8_STAGE(PG8_SA(1, 1), a1 + hstep, voffA);
;             PG8_WAIT_V(8); PG8_WAIT_L(0); PG8_BAR; PG8_MMA(0, 0, At, B0); PG8_MMA(0, 1, At, B1); PG8_BAR; PG8_SCHED;
;             PG8_LDA(At, 0, 1); PG8_STAGE(PG8_SB(0, 0), b2, voffB); PG8_STAGE(PG8_SB(0, 1), b2 + hstep, voffB); PG8_STAGE(PG8_SA(0, 0), a2, voffA);
;             PG8_WAIT_V(8); PG8_WAIT_L(0); PG8_BAR; PG8_MMA(1, 0, At, B0); PG8_MMA(1, 1, At, B1); PG8_BAR; PG8_SCHED;
.LBB0_959:
	ds_read_b128 v[130:133], v164
	ds_read_b128 v[134:137], v164 offset:1024
	ds_read_b128 v[154:157], v164 offset:2048
	ds_read_b128 v[158:161], v164 offset:3072
	ds_read_b128 v[168:171], v165
	ds_read_b128 v[172:175], v165 offset:1024
	ds_read_b128 v[176:179], v165 offset:2048
	ds_read_b128 v[180:183], v165 offset:3072
	s_add_u32 s30, s28, 0xfff00080
	s_addc_u32 s31, s29, -1
	s_cmp_eq_u32 s51, 60
	s_cselect_b32 s35, s13, s31
	s_cselect_b32 s34, s47, s30
	s_cselect_b32 s31, s11, s50
	s_cselect_b32 s30, s48, s49
	s_add_i32 m0, s27, 0xc000
	ds_read_b128 v[184:187], v166
	ds_read_b128 v[188:191], v166 offset:1024
	ds_read_b128 v[192:195], v166 offset:2048
	ds_read_b128 v[200:203], v166 offset:3072
	ds_read_b128 v[204:207], v166 offset:4096
	ds_read_b128 v[208:211], v166 offset:5120
	ds_read_b128 v[212:215], v166 offset:6144
	ds_read_b128 v[216:219], v166 offset:7168
	global_load_lds_dwordx4 v146, s[28:29]
	s_add_i32 m0, s27, 0xe000
	s_nop 0
	global_load_lds_dwordx4 v148, s[28:29]
	s_waitcnt vmcnt(8)
	s_waitcnt lgkmcnt(0)
	s_barrier
	v_mfma_f32_16x16x32_bf16 v[126:129], v[130:133], v[184:187], v[126:129]
	v_mfma_f32_16x16x32_bf16 v[122:125], v[154:157], v[184:187], v[122:125]
	v_mfma_f32_16x16x32_bf16 v[118:121], v[130:133], v[192:195], v[118:121]
	v_mfma_f32_16x16x32_bf16 v[114:117], v[154:157], v[192:195], v[114:117]
	v_mfma_f32_16x16x32_bf16 v[110:113], v[130:133], v[204:207], v[110:113]
	v_mfma_f32_16x16x32_bf16 v[102:105], v[154:157], v[204:207], v[102:105]
	v_mfma_f32_16x16x32_bf16 v[82:85], v[130:133], v[212:215], v[82:85]
	v_mfma_f32_16x16x32_bf16 v[74:77], v[154:157], v[212:215], v[74:77]
	v_mfma_f32_16x16x32_bf16 v[126:129], v[134:137], v[188:191], v[126:129]
	v_mfma_f32_16x16x32_bf16 v[122:125], v[158:161], v[188:191], v[122:125]
	v_mfma_f32_16x16x32_bf16 v[118:121], v[134:137], v[200:203], v[118:121]
	v_mfma_f32_16x16x32_bf16 v[114:117], v[158:161], v[200:203], v[114:117]
	v_mfma_f32_16x16x32_bf16 v[110:113], v[134:137], v[208:211], v[110:113]
	v_mfma_f32_16x16x32_bf16 v[102:105], v[158:161], v[208:211], v[102:105]
	v_mfma_f32_16x16x32_bf16 v[82:85], v[134:137], v[216:219], v[82:85]
	v_mfma_f32_16x16x32_bf16 v[74:77], v[158:161], v[216:219], v[74:77]
	v_mfma_f32_16x16x32_bf16 v[106:109], v[168:171], v[184:187], v[106:109]
	v_mfma_f32_16x16x32_bf16 v[98:101], v[176:179], v[184:187], v[98:101]
	v_mfma_f32_16x16x32_bf16 v[94:97], v[168:171], v[192:195], v[94:97]
	v_mfma_f32_16x16x32_bf16 v[90:93], v[176:179], v[192:195], v[90:93]
	v_mfma_f32_16x16x32_bf16 v[86:89], v[168:171], v[204:207], v[86:89]
	v_mfma_f32_16x16x32_bf16 v[78:81], v[176:179], v[204:207], v[78:81]
	v_mfma_f32_16x16x32_bf16 v[70:73], v[168:171], v[212:215], v[70:73]
	v_mfma_f32_16x16x32_bf16 v[66:69], v[176:179], v[212:215], v[66:69]
	v_mfma_f32_16x16x32_bf16 v[106:109], v[172:175], v[188:191], v[106:109]
	v_mfma_f32_16x16x32_bf16 v[98:101], v[180:183], v[188:191], v[98:101]
	v_mfma_f32_16x16x32_bf16 v[94:97], v[172:175], v[200:203], v[94:97]
	v_mfma_f32_16x16x32_bf16 v[90:93], v[180:183], v[200:203], v[90:93]
	v_mfma_f32_16x16x32_bf16 v[86:89], v[172:175], v[208:211], v[86:89]
	v_mfma_f32_16x16x32_bf16 v[78:81], v[180:183], v[208:211], v[78:81]
	v_mfma_f32_16x16x32_bf16 v[70:73], v[172:175], v[216:219], v[70:73]
	v_mfma_f32_16x16x32_bf16 v[66:69], v[180:183], v[216:219], v[66:69]
	s_barrier
	s_add_i32 s52, s44, s36
	v_lshl_add_u64 v[196:197], s[30:31], 0, v[140:141]
	s_mov_b32 m0, s52
	ds_read_b128 v[184:187], v166 offset:16384
	ds_read_b128 v[188:191], v166 offset:17408
	ds_read_b128 v[192:195], v166 offset:18432
	ds_read_b128 v[200:203], v166 offset:19456
	ds_read_b128 v[204:207], v166 offset:20480
	ds_read_b128 v[208:211], v166 offset:21504
	ds_read_b128 v[212:215], v166 offset:22528
	ds_read_b128 v[216:219], v166 offset:23552
	global_load_lds_dwordx4 v140, s[30:31]
	s_add_i32 m0, s52, 0x2000
	s_add_u32 s52, s30, 0x100000
	v_lshl_add_u64 v[220:221], s[30:31], 0, v[144:145]
	s_addc_u32 s53, s31, 0
	s_add_i32 s54, s45, s36
	global_load_lds_dwordx4 v144, s[30:31]
	s_mov_b32 m0, s54
	v_lshl_add_u64 v[224:225], s[34:35], 0, v[142:143]
	global_load_lds_dwordx4 v140, s[52:53]
	s_add_i32 m0, s54, 0x2000
	s_nop 0
	global_load_lds_dwordx4 v144, s[52:53]
	v_lshl_add_u64 v[222:223], s[34:35], 0, v[138:139]
	s_mov_b32 m0, s27
	s_nop 0
	global_load_lds_dwordx4 v138, s[34:35]
	s_mov_b32 m0, s37
	s_nop 0
	global_load_lds_dwordx4 v142, s[34:35]
	s_waitcnt vmcnt(8)
	s_waitcnt lgkmcnt(0)
	s_barrier
	v_mfma_f32_16x16x32_bf16 v[62:65], v[130:133], v[184:187], v[62:65]
	v_mfma_f32_16x16x32_bf16 v[58:61], v[154:157], v[184:187], v[58:61]
	v_mfma_f32_16x16x32_bf16 v[50:53], v[130:133], v[192:195], v[50:53]
	v_mfma_f32_16x16x32_bf16 v[42:45], v[154:157], v[192:195], v[42:45]
	v_mfma_f32_16x16x32_bf16 v[34:37], v[130:133], v[204:207], v[34:37]
	v_mfma_f32_16x16x32_bf16 v[26:29], v[154:157], v[204:207], v[26:29]
	v_mfma_f32_16x16x32_bf16 v[18:21], v[130:133], v[212:215], v[18:21]
	v_mfma_f32_16x16x32_bf16 v[10:13], v[154:157], v[212:215], v[10:13]
	v_mfma_f32_16x16x32_bf16 v[62:65], v[134:137], v[188:191], v[62:65]
	v_mfma_f32_16x16x32_bf16 v[58:61], v[158:161], v[188:191], v[58:61]
	v_mfma_f32_16x16x32_bf16 v[50:53], v[134:137], v[200:203], v[50:53]
	v_mfma_f32_16x16x32_bf16 v[42:45], v[158:161], v[200:203], v[42:45]
	v_mfma_f32_16x16x32_bf16 v[34:37], v[134:137], v[208:211], v[34:37]
	v_mfma_f32_16x16x32_bf16 v[26:29], v[158:161], v[208:211], v[26:29]
	v_mfma_f32_16x16x32_bf16 v[18:21], v[134:137], v[216:219], v[18:21]
	v_mfma_f32_16x16x32_bf16 v[10:13], v[158:161], v[216:219], v[10:13]
	v_mfma_f32_16x16x32_bf16 v[54:57], v[168:171], v[184:187], v[54:57]
	v_mfma_f32_16x16x32_bf16 v[46:49], v[176:179], v[184:187], v[46:49]
	v_mfma_f32_16x16x32_bf16 v[38:41], v[168:171], v[192:195], v[38:41]
	v_mfma_f32_16x16x32_bf16 v[30:33], v[176:179], v[192:195], v[30:33]
	v_mfma_f32_16x16x32_bf16 v[22:25], v[168:171], v[204:207], v[22:25]
	v_mfma_f32_16x16x32_bf16 v[14:17], v[176:179], v[204:207], v[14:17]
	v_mfma_f32_16x16x32_bf16 v[6:9], v[168:171], v[212:215], v[6:9]
	v_mfma_f32_16x16x32_bf16 v[2:5], v[176:179], v[212:215], v[2:5]
	v_mfma_f32_16x16x32_bf16 v[54:57], v[172:175], v[188:191], v[54:57]
	v_mfma_f32_16x16x32_bf16 v[46:49], v[180:183], v[188:191], v[46:49]
	v_mfma_f32_16x16x32_bf16 v[38:41], v[172:175], v[200:203], v[38:41]
	v_mfma_f32_16x16x32_bf16 v[30:33], v[180:183], v[200:203], v[30:33]
	v_mfma_f32_16x16x32_bf16 v[22:25], v[172:175], v[208:211], v[22:25]
	v_mfma_f32_16x16x32_bf16 v[14:17], v[180:183], v[208:211], v[14:17]
	v_mfma_f32_16x16x32_bf16 v[6:9], v[172:175], v[216:219], v[6:9]
	v_mfma_f32_16x16x32_bf16 v[2:5], v[180:183], v[216:219], v[2:5]
	s_barrier
; #define PG8_STAGE(bufoff, gbase, voff) do { _Pragma("unroll") for (int _i = 0; _i < 2; ++_i) \
;         __builtin_amdgcn_global_load_lds((const unsigned*)((const char*)(gbase) + (voff)[_i]), (PG8_LAS unsigned*)(lds + (bufoff) + ldsw + _i * 8192), 16, 0, 0); } while (0)
; #define PG8_LDA(dst, b, h) do { _Pragma("unroll") for (int m = 0; m < 4; ++m) _Pragma("unroll") for (int k = 0; k < 2; ++k) dst[m][k] = *(const PG8_LAS bf16x8*)(lds + PG8_SA(b, h) + aoff + m * 2048 + k * 1024); } while (0)
; #define PG8_LDB(dst, b, h) do { _Pragma("unroll") for (int n = 0; n < 2; ++n) _Pragma("unroll") for (int k = 0; k < 2; ++k) dst[n][k] = *(const PG8_LAS bf16x8*)(lds + PG8_SB(b, h) + boff + n * 2048 + k * 1024); } while (0)
; #define PG8_MMA(ai, bj, At, Bt) do { __builtin_amdgcn_s_setprio(1); _Pragma("unroll") for (int m = 0; m < 4; ++m) _Pragma("unroll") for (int n = 0; n < 2; ++n) _Pragma("unroll") for (int k = 0; k < 2; ++k) \
;         acc[ai][bj][m][n] = __builtin_amdgcn_mfma_f32_16x16x32_bf16(Bt[n][k], At[m][k], acc[ai][bj][m][n], 0, 0, 0); __builtin_amdgcn_s_setprio(0); } while (0)
; #define PG8_WAIT_V(n) asm volatile("s_waitcnt vmcnt(" #n ")" ::: "memory")
; #define PG8_WAIT_L(n) asm volatile("s_waitcnt lgkmcnt(" #n ")" ::: "memory")
; #define PG8_BAR __builtin_amdgcn_s_barrier()
; #define PG8_SCHED __builtin_amdgcn_sched_barrier(0)
; template <class Epi, class Sched, bool ALIGN_EPI = false, bool SP2 = false>
; __device__ __forceinline__ void gemm_phase(PG8_LAS unsigned char* lds, const Gemm g, const Sched& S, const Epi& E) {
;     ...
;             PG8_LDB(B0, 1, 0); PG8_LDB(B1, 1, 1); PG8_SCHED; PG8_LDA(At, 1, 0); PG8_STAGE(PG8_SA(0, 1), a2 + hstep, voffA);
;             PG8_WAIT_V(8); PG8_WAIT_L(0); PG8_BAR; PG8_MMA(0, 0, At, B0); PG8_MMA(0, 1, At, B1); PG8_BAR; PG8_SCHED;
;             PG8_LDA(At, 1, 1); PG8_STAGE(PG8_SB(1, 0), b3, voffB); PG8_STAGE(PG8_SB(1, 1), b3 + hstep, voffB); PG8_STAGE(PG8_SA(1, 0), a3, voffA);
;             PG8_WAIT_V(8); PG8_WAIT_L(0); PG8_BAR; PG8_MMA(1, 0, At, B0); PG8_MMA(1, 1, At, B1); PG8_BAR; PG8_SCHED;
	s_add_i32 s52, 0, 0x18000
	s_add_i32 s53, 0, 0x1c000
	v_add_u32_e32 v158, s52, v162
	v_add_u32_e32 v167, s53, v162
	ds_read_b128 v[130:133], v158
	ds_read_b128 v[134:137], v158 offset:1024
	ds_read_b128 v[154:157], v158 offset:2048
	ds_read_b128 v[158:161], v158 offset:3072
	ds_read_b128 v[168:171], v167
	ds_read_b128 v[172:175], v167 offset:1024
	ds_read_b128 v[176:179], v167 offset:2048
	ds_read_b128 v[180:183], v167 offset:3072
	s_add_u32 s34, s34, 0x100000
	s_addc_u32 s35, s35, 0
	s_mov_b32 m0, s38
	ds_read_b128 v[184:187], v166 offset:32768
	ds_read_b128 v[188:191], v166 offset:33792
	ds_read_b128 v[192:195], v166 offset:34816
	ds_read_b128 v[200:203], v166 offset:35840
	ds_read_b128 v[204:207], v166 offset:36864
	ds_read_b128 v[208:211], v166 offset:37888
	ds_read_b128 v[212:215], v166 offset:38912
	ds_read_b128 v[216:219], v166 offset:39936
	global_load_lds_dwordx4 v138, s[34:35]
	s_mov_b32 m0, s39
	s_nop 0
	global_load_lds_dwordx4 v142, s[34:35]
	s_waitcnt vmcnt(8)
	s_waitcnt lgkmcnt(0)
	s_barrier
	v_mfma_f32_16x16x32_bf16 v[126:129], v[130:133], v[184:187], v[126:129]
	v_mfma_f32_16x16x32_bf16 v[122:125], v[154:157], v[184:187], v[122:125]
	v_mfma_f32_16x16x32_bf16 v[118:121], v[130:133], v[192:195], v[118:121]
	v_mfma_f32_16x16x32_bf16 v[114:117], v[154:157], v[192:195], v[114:117]
	v_mfma_f32_16x16x32_bf16 v[110:113], v[130:133], v[204:207], v[110:113]
	v_mfma_f32_16x16x32_bf16 v[102:105], v[154:157], v[204:207], v[102:105]
	v_mfma_f32_16x16x32_bf16 v[82:85], v[130:133], v[212:215], v[82:85]
	v_mfma_f32_16x16x32_bf16 v[74:77], v[154:157], v[212:215], v[74:77]
	v_mfma_f32_16x16x32_bf16 v[126:129], v[134:137], v[188:191], v[126:129]
	v_mfma_f32_16x16x32_bf16 v[122:125], v[158:161], v[188:191], v[122:125]
	v_mfma_f32_16x16x32_bf16 v[118:121], v[134:137], v[200:203], v[118:121]
	v_mfma_f32_16x16x32_bf16 v[114:117], v[158:161], v[200:203], v[114:117]
	v_mfma_f32_16x16x32_bf16 v[110:113], v[134:137], v[208:211], v[110:113]
	v_mfma_f32_16x16x32_bf16 v[102:105], v[158:161], v[208:211], v[102:105]
	v_mfma_f32_16x16x32_bf16 v[82:85], v[134:137], v[216:219], v[82:85]
	v_mfma_f32_16x16x32_bf16 v[74:77], v[158:161], v[216:219], v[74:77]
	v_mfma_f32_16x16x32_bf16 v[106:109], v[168:171], v[184:187], v[106:109]
	v_mfma_f32_16x16x32_bf16 v[98:101], v[176:179], v[184:187], v[98:101]
	v_mfma_f32_16x16x32_bf16 v[94:97], v[168:171], v[192:195], v[94:97]
	v_mfma_f32_16x16x32_bf16 v[90:93], v[176:179], v[192:195], v[90:93]
	v_mfma_f32_16x16x32_bf16 v[86:89], v[168:171], v[204:207], v[86:89]
	v_mfma_f32_16x16x32_bf16 v[78:81], v[176:179], v[204:207], v[78:81]
	v_mfma_f32_16x16x32_bf16 v[70:73], v[168:171], v[212:215], v[70:73]
	v_mfma_f32_16x16x32_bf16 v[66:69], v[176:179], v[212:215], v[66:69]
	v_mfma_f32_16x16x32_bf16 v[106:109], v[172:175], v[188:191], v[106:109]
	v_mfma_f32_16x16x32_bf16 v[98:101], v[180:183], v[188:191], v[98:101]
	v_mfma_f32_16x16x32_bf16 v[94:97], v[172:175], v[200:203], v[94:97]
	v_mfma_f32_16x16x32_bf16 v[90:93], v[180:183], v[200:203], v[90:93]
	v_mfma_f32_16x16x32_bf16 v[86:89], v[172:175], v[208:211], v[86:89]
	v_mfma_f32_16x16x32_bf16 v[78:81], v[180:183], v[208:211], v[78:81]
	v_mfma_f32_16x16x32_bf16 v[70:73], v[172:175], v[216:219], v[70:73]
	v_mfma_f32_16x16x32_bf16 v[66:69], v[180:183], v[216:219], v[66:69]
	s_barrier
	s_add_i32 s34, s52, s36
	v_lshl_add_u64 v[196:197], v[196:197], 0, s[6:7]
	s_mov_b32 m0, s34
	ds_read_b128 v[184:187], v166 offset:49152
	ds_read_b128 v[188:191], v166 offset:50176
	ds_read_b128 v[192:195], v166 offset:51200
	ds_read_b128 v[200:203], v166 offset:52224
	ds_read_b128 v[204:207], v166 offset:53248
	ds_read_b128 v[208:211], v166 offset:54272
	ds_read_b128 v[212:215], v166 offset:55296
	ds_read_b128 v[216:219], v166 offset:56320
	global_load_lds_dwordx4 v[196:197], off
	s_add_i32 m0, s34, 0x2000
	s_add_u32 s30, s30, 0x100080
	v_lshl_add_u64 v[196:197], v[220:221], 0, s[6:7]
	s_addc_u32 s31, s31, 0
	s_add_i32 s34, s53, s36
	global_load_lds_dwordx4 v[196:197], off
	s_mov_b32 m0, s34
	s_nop 0
	global_load_lds_dwordx4 v140, s[30:31]
	s_add_i32 m0, s34, 0x2000
	s_nop 0
	global_load_lds_dwordx4 v144, s[30:31]
	v_lshl_add_u64 v[196:197], v[222:223], 0, s[6:7]
	s_mov_b32 m0, s41
	s_nop 0
	global_load_lds_dwordx4 v[196:197], off
	v_lshl_add_u64 v[196:197], v[224:225], 0, s[6:7]
	s_mov_b32 m0, s42
	s_nop 0
	global_load_lds_dwordx4 v[196:197], off
	s_waitcnt vmcnt(8)
	s_waitcnt lgkmcnt(0)
	s_barrier
	v_mfma_f32_16x16x32_bf16 v[62:65], v[130:133], v[184:187], v[62:65]
	v_mfma_f32_16x16x32_bf16 v[58:61], v[154:157], v[184:187], v[58:61]
	v_mfma_f32_16x16x32_bf16 v[50:53], v[130:133], v[192:195], v[50:53]
	v_mfma_f32_16x16x32_bf16 v[42:45], v[154:157], v[192:195], v[42:45]
	v_mfma_f32_16x16x32_bf16 v[34:37], v[130:133], v[204:207], v[34:37]
	v_mfma_f32_16x16x32_bf16 v[26:29], v[154:157], v[204:207], v[26:29]
	v_mfma_f32_16x16x32_bf16 v[18:21], v[130:133], v[212:215], v[18:21]
	v_mfma_f32_16x16x32_bf16 v[10:13], v[154:157], v[212:215], v[10:13]
	v_mfma_f32_16x16x32_bf16 v[62:65], v[134:137], v[188:191], v[62:65]
	v_mfma_f32_16x16x32_bf16 v[58:61], v[158:161], v[188:191], v[58:61]
	v_mfma_f32_16x16x32_bf16 v[50:53], v[134:137], v[200:203], v[50:53]
	v_mfma_f32_16x16x32_bf16 v[42:45], v[158:161], v[200:203], v[42:45]
	v_mfma_f32_16x16x32_bf16 v[34:37], v[134:137], v[208:211], v[34:37]
	v_mfma_f32_16x16x32_bf16 v[26:29], v[158:161], v[208:211], v[26:29]
	v_mfma_f32_16x16x32_bf16 v[18:21], v[134:137], v[216:219], v[18:21]
	v_mfma_f32_16x16x32_bf16 v[10:13], v[158:161], v[216:219], v[10:13]
	v_mfma_f32_16x16x32_bf16 v[54:57], v[168:171], v[184:187], v[54:57]
	v_mfma_f32_16x16x32_bf16 v[46:49], v[176:179], v[184:187], v[46:49]
	v_mfma_f32_16x16x32_bf16 v[38:41], v[168:171], v[192:195], v[38:41]
	v_mfma_f32_16x16x32_bf16 v[30:33], v[176:179], v[192:195], v[30:33]
	v_mfma_f32_16x16x32_bf16 v[22:25], v[168:171], v[204:207], v[22:25]
	v_mfma_f32_16x16x32_bf16 v[14:17], v[176:179], v[204:207], v[14:17]
	v_mfma_f32_16x16x32_bf16 v[6:9], v[168:171], v[212:215], v[6:9]
	v_mfma_f32_16x16x32_bf16 v[2:5], v[176:179], v[212:215], v[2:5]
	v_mfma_f32_16x16x32_bf16 v[54:57], v[172:175], v[188:191], v[54:57]
	v_mfma_f32_16x16x32_bf16 v[46:49], v[180:183], v[188:191], v[46:49]
	v_mfma_f32_16x16x32_bf16 v[38:41], v[172:175], v[200:203], v[38:41]
	v_mfma_f32_16x16x32_bf16 v[30:33], v[180:183], v[200:203], v[30:33]
	v_mfma_f32_16x16x32_bf16 v[22:25], v[172:175], v[208:211], v[22:25]
	v_mfma_f32_16x16x32_bf16 v[14:17], v[180:183], v[208:211], v[14:17]
	v_mfma_f32_16x16x32_bf16 v[6:9], v[172:175], v[216:219], v[6:9]
	v_mfma_f32_16x16x32_bf16 v[2:5], v[180:183], v[216:219], v[2:5]
	s_barrier
	s_add_i32 s51, s51, 2
	s_add_u32 s28, s28, 0x100
	s_addc_u32 s29, s29, 0
	s_add_u32 s49, s49, 0x100
	s_addc_u32 s50, s50, 0
	s_cmp_gt_u32 s51, 61
	s_cbranch_scc0 .LBB0_959
	s_and_b64 vcc, exec, s[8:9]
	s_cbranch_vccz .LBB0_962
	s_barrier

; #define PG8_STAGE(bufoff, gbase, voff) do { _Pragma("unroll") for (int _i = 0; _i < 2; ++_i) \
;         __builtin_amdgcn_global_load_lds((const unsigned*)((const char*)(gbase) + (voff)[_i]), (PG8_LAS unsigned*)(lds + (bufoff) + ldsw + _i * 8192), 16, 0, 0); } while (0)
; #define PG8_LDA(dst, b, h) do { _Pragma("unroll") for (int m = 0; m < 4; ++m) _Pragma("unroll") for (int k = 0; k < 2; ++k) dst[m][k] = *(const PG8_LAS bf16x8*)(lds + PG8_SA(b, h) + aoff + m * 2048 + k * 1024); } while (0)
; #define PG8_LDB(dst, b, h) do { _Pragma("unroll") for (int n = 0; n < 2; ++n) _Pragma("unroll") for (int k = 0; k < 2; ++k) dst[n][k] = *(const PG8_LAS bf16x8*)(lds + PG8_SB(b, h) + boff + n * 2048 + k * 1024); } while (0)
; #define PG8_MMA(ai, bj, At, Bt) do { __builtin_amdgcn_s_setprio(1); _Pragma("unroll") for (int m = 0; m < 4; ++m) _Pragma("unroll") for (int n = 0; n < 2; ++n) _Pragma("unroll") for (int k = 0; k < 2; ++k) \
;         acc[ai][bj][m][n] = __builtin_amdgcn_mfma_f32_16x16x32_bf16(Bt[n][k], At[m][k], acc[ai][bj][m][n], 0, 0, 0); __builtin_amdgcn_s_setprio(0); } while (0)
; #define PG8_WAIT_V(n) asm volatile("s_waitcnt vmcnt(" #n ")" ::: "memory")
; #define PG8_WAIT_L(n) asm volatile("s_waitcnt lgkmcnt(" #n ")" ::: "memory")
; #define PG8_BAR __builtin_amdgcn_s_barrier()
; #define PG8_SCHED __builtin_amdgcn_sched_barrier(0)
; template <class Epi, class Sched, bool ALIGN_EPI = false, bool SP2 = false>
; __device__ __forceinline__ void gemm_phase(PG8_LAS unsigned char* lds, const Gemm g, const Sched& S, const Epi& E) {
;     ...
;             PG8_LDB(B0, 0, 0); PG8_LDB(B1, 0, 1); PG8_SCHED; PG8_LDA(At, 0, 0); PG8_STAGE(PG8_SA(1, 1), a1 + hstep, voffA);
;             PG8_WAIT_V(8); PG8_WAIT_L(0); PG8_BAR; PG8_MMA(0, 0, At, B0); PG8_MMA(0, 1, At, B1); PG8_BAR; PG8_SCHED;
;             PG8_LDA(At, 0, 1); PG8_STAGE(PG8_SB(0, 0), b2, voffB); PG8_STAGE(PG8_SB(0, 1), b2 + hstep, voffB); PG8_STAGE(PG8_SA(0, 0), a2, voffA);
;             PG8_WAIT_V(8); PG8_WAIT_L(0); PG8_BAR; PG8_MMA(1, 0, At, B0); PG8_MMA(1, 1, At, B1); PG8_BAR; PG8_SCHED;
.LBB0_1081:
	ds_read_b128 v[154:157], v150
	ds_read_b128 v[158:161], v150 offset:1024
	ds_read_b128 v[162:165], v150 offset:2048
	ds_read_b128 v[166:169], v150 offset:3072
	ds_read_b128 v[170:173], v151
	ds_read_b128 v[174:177], v151 offset:1024
	ds_read_b128 v[178:181], v151 offset:2048
	ds_read_b128 v[182:185], v151 offset:3072
	s_add_u32 s34, s30, 0xfff00080
	s_addc_u32 s35, s31, -1
	s_cmp_eq_u32 s55, 60
	s_cselect_b32 s37, s15, s35
	s_cselect_b32 s36, s51, s34
	s_cselect_b32 s35, s13, s54
	s_cselect_b32 s34, s52, s53
	s_add_i32 m0, s29, 0xc000
	ds_read_b128 v[186:189], v152
	ds_read_b128 v[190:193], v152 offset:1024
	ds_read_b128 v[194:197], v152 offset:2048
	ds_read_b128 v[200:203], v152 offset:3072
	ds_read_b128 v[204:207], v152 offset:4096
	ds_read_b128 v[208:211], v152 offset:5120
	ds_read_b128 v[212:215], v152 offset:6144
	ds_read_b128 v[216:219], v152 offset:7168
	global_load_lds_dwordx4 v138, s[30:31]
	s_add_i32 m0, s29, 0xe000
	s_nop 0
	global_load_lds_dwordx4 v140, s[30:31]
	s_waitcnt vmcnt(8)
	s_waitcnt lgkmcnt(0)
	s_barrier
	v_mfma_f32_16x16x32_bf16 v[126:129], v[154:157], v[186:189], v[126:129]
	v_mfma_f32_16x16x32_bf16 v[122:125], v[162:165], v[186:189], v[122:125]
	v_mfma_f32_16x16x32_bf16 v[110:113], v[154:157], v[194:197], v[110:113]
	v_mfma_f32_16x16x32_bf16 v[106:109], v[162:165], v[194:197], v[106:109]
	v_mfma_f32_16x16x32_bf16 v[94:97], v[154:157], v[204:207], v[94:97]
	v_mfma_f32_16x16x32_bf16 v[90:93], v[162:165], v[204:207], v[90:93]
	v_mfma_f32_16x16x32_bf16 v[78:81], v[154:157], v[212:215], v[78:81]
	v_mfma_f32_16x16x32_bf16 v[74:77], v[162:165], v[212:215], v[74:77]
	v_mfma_f32_16x16x32_bf16 v[126:129], v[158:161], v[190:193], v[126:129]
	v_mfma_f32_16x16x32_bf16 v[122:125], v[166:169], v[190:193], v[122:125]
	v_mfma_f32_16x16x32_bf16 v[110:113], v[158:161], v[200:203], v[110:113]
	v_mfma_f32_16x16x32_bf16 v[106:109], v[166:169], v[200:203], v[106:109]
	v_mfma_f32_16x16x32_bf16 v[94:97], v[158:161], v[208:211], v[94:97]
	v_mfma_f32_16x16x32_bf16 v[90:93], v[166:169], v[208:211], v[90:93]
	v_mfma_f32_16x16x32_bf16 v[78:81], v[158:161], v[216:219], v[78:81]
	v_mfma_f32_16x16x32_bf16 v[74:77], v[166:169], v[216:219], v[74:77]
	v_mfma_f32_16x16x32_bf16 v[118:121], v[170:173], v[186:189], v[118:121]
	v_mfma_f32_16x16x32_bf16 v[114:117], v[178:181], v[186:189], v[114:117]
	v_mfma_f32_16x16x32_bf16 v[102:105], v[170:173], v[194:197], v[102:105]
	v_mfma_f32_16x16x32_bf16 v[98:101], v[178:181], v[194:197], v[98:101]
	v_mfma_f32_16x16x32_bf16 v[86:89], v[170:173], v[204:207], v[86:89]
	v_mfma_f32_16x16x32_bf16 v[82:85], v[178:181], v[204:207], v[82:85]
	v_mfma_f32_16x16x32_bf16 v[70:73], v[170:173], v[212:215], v[70:73]
	v_mfma_f32_16x16x32_bf16 v[66:69], v[178:181], v[212:215], v[66:69]
	v_mfma_f32_16x16x32_bf16 v[118:121], v[174:177], v[190:193], v[118:121]
	v_mfma_f32_16x16x32_bf16 v[114:117], v[182:185], v[190:193], v[114:117]
	v_mfma_f32_16x16x32_bf16 v[102:105], v[174:177], v[200:203], v[102:105]
	v_mfma_f32_16x16x32_bf16 v[98:101], v[182:185], v[200:203], v[98:101]
	v_mfma_f32_16x16x32_bf16 v[86:89], v[174:177], v[208:211], v[86:89]
	v_mfma_f32_16x16x32_bf16 v[82:85], v[182:185], v[208:211], v[82:85]
	v_mfma_f32_16x16x32_bf16 v[70:73], v[174:177], v[216:219], v[70:73]
	v_mfma_f32_16x16x32_bf16 v[66:69], v[182:185], v[216:219], v[66:69]
	s_barrier
	s_add_i32 s56, s47, s33
	v_lshl_add_u64 v[146:147], s[34:35], 0, v[134:135]
	s_mov_b32 m0, s56
	ds_read_b128 v[186:189], v152 offset:16384
	ds_read_b128 v[190:193], v152 offset:17408
	ds_read_b128 v[194:197], v152 offset:18432
	ds_read_b128 v[200:203], v152 offset:19456
	ds_read_b128 v[204:207], v152 offset:20480
	ds_read_b128 v[208:211], v152 offset:21504
	ds_read_b128 v[212:215], v152 offset:22528
	ds_read_b128 v[216:219], v152 offset:23552
	global_load_lds_dwordx4 v134, s[34:35]
	s_add_i32 m0, s56, 0x2000
	s_add_u32 s56, s34, 0x100000
	v_lshl_add_u64 v[220:221], s[34:35], 0, v[130:131]
	s_addc_u32 s57, s35, 0
	s_add_i32 s58, s48, s33
	global_load_lds_dwordx4 v130, s[34:35]
	s_mov_b32 m0, s58
	v_lshl_add_u64 v[224:225], s[36:37], 0, v[132:133]
	global_load_lds_dwordx4 v134, s[56:57]
	s_add_i32 m0, s58, 0x2000
	s_nop 0
	global_load_lds_dwordx4 v130, s[56:57]
	v_lshl_add_u64 v[222:223], s[36:37], 0, v[136:137]
	s_mov_b32 m0, s29
	s_nop 0
	global_load_lds_dwordx4 v136, s[36:37]
	s_mov_b32 m0, s40
	s_nop 0
	global_load_lds_dwordx4 v132, s[36:37]
	s_waitcnt vmcnt(8)
	s_waitcnt lgkmcnt(0)
	s_barrier
	v_mfma_f32_16x16x32_bf16 v[62:65], v[154:157], v[186:189], v[62:65]
	v_mfma_f32_16x16x32_bf16 v[58:61], v[162:165], v[186:189], v[58:61]
	v_mfma_f32_16x16x32_bf16 v[46:49], v[154:157], v[194:197], v[46:49]
	v_mfma_f32_16x16x32_bf16 v[42:45], v[162:165], v[194:197], v[42:45]
	v_mfma_f32_16x16x32_bf16 v[30:33], v[154:157], v[204:207], v[30:33]
	v_mfma_f32_16x16x32_bf16 v[26:29], v[162:165], v[204:207], v[26:29]
	v_mfma_f32_16x16x32_bf16 v[14:17], v[154:157], v[212:215], v[14:17]
	v_mfma_f32_16x16x32_bf16 v[10:13], v[162:165], v[212:215], v[10:13]
	v_mfma_f32_16x16x32_bf16 v[62:65], v[158:161], v[190:193], v[62:65]
	v_mfma_f32_16x16x32_bf16 v[58:61], v[166:169], v[190:193], v[58:61]
	v_mfma_f32_16x16x32_bf16 v[46:49], v[158:161], v[200:203], v[46:49]
	v_mfma_f32_16x16x32_bf16 v[42:45], v[166:169], v[200:203], v[42:45]
	v_mfma_f32_16x16x32_bf16 v[30:33], v[158:161], v[208:211], v[30:33]
	v_mfma_f32_16x16x32_bf16 v[26:29], v[166:169], v[208:211], v[26:29]
	v_mfma_f32_16x16x32_bf16 v[14:17], v[158:161], v[216:219], v[14:17]
	v_mfma_f32_16x16x32_bf16 v[10:13], v[166:169], v[216:219], v[10:13]
	v_mfma_f32_16x16x32_bf16 v[54:57], v[170:173], v[186:189], v[54:57]
	v_mfma_f32_16x16x32_bf16 v[50:53], v[178:181], v[186:189], v[50:53]
	v_mfma_f32_16x16x32_bf16 v[38:41], v[170:173], v[194:197], v[38:41]
	v_mfma_f32_16x16x32_bf16 v[34:37], v[178:181], v[194:197], v[34:37]
	v_mfma_f32_16x16x32_bf16 v[22:25], v[170:173], v[204:207], v[22:25]
	v_mfma_f32_16x16x32_bf16 v[18:21], v[178:181], v[204:207], v[18:21]
	v_mfma_f32_16x16x32_bf16 v[6:9], v[170:173], v[212:215], v[6:9]
	v_mfma_f32_16x16x32_bf16 v[2:5], v[178:181], v[212:215], v[2:5]
	v_mfma_f32_16x16x32_bf16 v[54:57], v[174:177], v[190:193], v[54:57]
	v_mfma_f32_16x16x32_bf16 v[50:53], v[182:185], v[190:193], v[50:53]
	v_mfma_f32_16x16x32_bf16 v[38:41], v[174:177], v[200:203], v[38:41]
	v_mfma_f32_16x16x32_bf16 v[34:37], v[182:185], v[200:203], v[34:37]
	v_mfma_f32_16x16x32_bf16 v[22:25], v[174:177], v[208:211], v[22:25]
	v_mfma_f32_16x16x32_bf16 v[18:21], v[182:185], v[208:211], v[18:21]
	v_mfma_f32_16x16x32_bf16 v[6:9], v[174:177], v[216:219], v[6:9]
	v_mfma_f32_16x16x32_bf16 v[2:5], v[182:185], v[216:219], v[2:5]
	s_barrier
; #define PG8_STAGE(bufoff, gbase, voff) do { _Pragma("unroll") for (int _i = 0; _i < 2; ++_i) \
;         __builtin_amdgcn_global_load_lds((const unsigned*)((const char*)(gbase) + (voff)[_i]), (PG8_LAS unsigned*)(lds + (bufoff) + ldsw + _i * 8192), 16, 0, 0); } while (0)
; #define PG8_LDA(dst, b, h) do { _Pragma("unroll") for (int m = 0; m < 4; ++m) _Pragma("unroll") for (int k = 0; k < 2; ++k) dst[m][k] = *(const PG8_LAS bf16x8*)(lds + PG8_SA(b, h) + aoff + m * 2048 + k * 1024); } while (0)
; #define PG8_LDB(dst, b, h) do { _Pragma("unroll") for (int n = 0; n < 2; ++n) _Pragma("unroll") for (int k = 0; k < 2; ++k) dst[n][k] = *(const PG8_LAS bf16x8*)(lds + PG8_SB(b, h) + boff + n * 2048 + k * 1024); } while (0)
; #define PG8_MMA(ai, bj, At, Bt) do { __builtin_amdgcn_s_setprio(1); _Pragma("unroll") for (int m = 0; m < 4; ++m) _Pragma("unroll") for (int n = 0; n < 2; ++n) _Pragma("unroll") for (int k = 0; k < 2; ++k) \
;         acc[ai][bj][m][n] = __builtin_amdgcn_mfma_f32_16x16x32_bf16(Bt[n][k], At[m][k], acc[ai][bj][m][n], 0, 0, 0); __builtin_amdgcn_s_setprio(0); } while (0)
; #define PG8_WAIT_V(n) asm volatile("s_waitcnt vmcnt(" #n ")" ::: "memory")
; #define PG8_WAIT_L(n) asm volatile("s_waitcnt lgkmcnt(" #n ")" ::: "memory")
; #define PG8_BAR __builtin_amdgcn_s_barrier()
; #define PG8_SCHED __builtin_amdgcn_sched_barrier(0)
; template <class Epi, class Sched, bool ALIGN_EPI = false, bool SP2 = false>
; __device__ __forceinline__ void gemm_phase(PG8_LAS unsigned char* lds, const Gemm g, const Sched& S, const Epi& E) {
;     ...
;         for (int t = 0; t < nt; t += 2) {
;             const bool last = (t == nt - 2);
;             const char* a1 = cA + (size_t)(t + 1) * kstep;
;             const char* a2 = last ? nA : cA + (size_t)(t + 2) * kstep; const char* b2 = last ? nB : cB + (size_t)(t + 2) * kstep;
;     ...
;             PG8_LDB(B0, 1, 0); PG8_LDB(B1, 1, 1); PG8_SCHED; PG8_LDA(At, 1, 0); PG8_STAGE(PG8_SA(0, 1), a2 + hstep, voffA);
;             PG8_WAIT_V(8); PG8_WAIT_L(0); PG8_BAR; PG8_MMA(0, 0, At, B0); PG8_MMA(0, 1, At, B1); PG8_BAR; PG8_SCHED;
;             PG8_LDA(At, 1, 1); PG8_STAGE(PG8_SB(1, 0), b3, voffB); PG8_STAGE(PG8_SB(1, 1), b3 + hstep, voffB); PG8_STAGE(PG8_SA(1, 0), a3, voffA);
;             PG8_WAIT_V(8); PG8_WAIT_L(0); PG8_BAR; PG8_MMA(1, 0, At, B0); PG8_MMA(1, 1, At, B1); PG8_BAR; PG8_SCHED;
	s_add_i32 s56, 0, 0x18000
	v_add_u32_e32 v153, s56, v148
	s_add_i32 s57, 0, 0x1c000
	ds_read_b128 v[154:157], v153
	ds_read_b128 v[158:161], v153 offset:1024
	ds_read_b128 v[162:165], v153 offset:2048
	ds_read_b128 v[166:169], v153 offset:3072
	v_add_u32_e32 v153, s57, v148
	ds_read_b128 v[170:173], v153
	ds_read_b128 v[174:177], v153 offset:1024
	ds_read_b128 v[178:181], v153 offset:2048
	ds_read_b128 v[182:185], v153 offset:3072
	s_add_u32 s36, s36, 0x100000
	s_addc_u32 s37, s37, 0
	s_mov_b32 m0, s41
	ds_read_b128 v[186:189], v152 offset:32768
	ds_read_b128 v[190:193], v152 offset:33792
	ds_read_b128 v[194:197], v152 offset:34816
	ds_read_b128 v[200:203], v152 offset:35840
	ds_read_b128 v[204:207], v152 offset:36864
	ds_read_b128 v[208:211], v152 offset:37888
	ds_read_b128 v[212:215], v152 offset:38912
	ds_read_b128 v[216:219], v152 offset:39936
	global_load_lds_dwordx4 v136, s[36:37]
	s_mov_b32 m0, s42
	s_nop 0
	global_load_lds_dwordx4 v132, s[36:37]
	s_waitcnt vmcnt(8)
	s_waitcnt lgkmcnt(0)
	s_barrier
	v_mfma_f32_16x16x32_bf16 v[126:129], v[154:157], v[186:189], v[126:129]
	v_mfma_f32_16x16x32_bf16 v[122:125], v[162:165], v[186:189], v[122:125]
	v_mfma_f32_16x16x32_bf16 v[110:113], v[154:157], v[194:197], v[110:113]
	v_mfma_f32_16x16x32_bf16 v[106:109], v[162:165], v[194:197], v[106:109]
	v_mfma_f32_16x16x32_bf16 v[94:97], v[154:157], v[204:207], v[94:97]
	v_mfma_f32_16x16x32_bf16 v[90:93], v[162:165], v[204:207], v[90:93]
	v_mfma_f32_16x16x32_bf16 v[78:81], v[154:157], v[212:215], v[78:81]
	v_mfma_f32_16x16x32_bf16 v[74:77], v[162:165], v[212:215], v[74:77]
	v_mfma_f32_16x16x32_bf16 v[126:129], v[158:161], v[190:193], v[126:129]
	v_mfma_f32_16x16x32_bf16 v[122:125], v[166:169], v[190:193], v[122:125]
	v_mfma_f32_16x16x32_bf16 v[110:113], v[158:161], v[200:203], v[110:113]
	v_mfma_f32_16x16x32_bf16 v[106:109], v[166:169], v[200:203], v[106:109]
	v_mfma_f32_16x16x32_bf16 v[94:97], v[158:161], v[208:211], v[94:97]
	v_mfma_f32_16x16x32_bf16 v[90:93], v[166:169], v[208:211], v[90:93]
	v_mfma_f32_16x16x32_bf16 v[78:81], v[158:161], v[216:219], v[78:81]
	v_mfma_f32_16x16x32_bf16 v[74:77], v[166:169], v[216:219], v[74:77]
	v_mfma_f32_16x16x32_bf16 v[118:121], v[170:173], v[186:189], v[118:121]
	v_mfma_f32_16x16x32_bf16 v[114:117], v[178:181], v[186:189], v[114:117]
	v_mfma_f32_16x16x32_bf16 v[102:105], v[170:173], v[194:197], v[102:105]
	v_mfma_f32_16x16x32_bf16 v[98:101], v[178:181], v[194:197], v[98:101]
	v_mfma_f32_16x16x32_bf16 v[86:89], v[170:173], v[204:207], v[86:89]
	v_mfma_f32_16x16x32_bf16 v[82:85], v[178:181], v[204:207], v[82:85]
	v_mfma_f32_16x16x32_bf16 v[70:73], v[170:173], v[212:215], v[70:73]
	v_mfma_f32_16x16x32_bf16 v[66:69], v[178:181], v[212:215], v[66:69]
	v_mfma_f32_16x16x32_bf16 v[118:121], v[174:177], v[190:193], v[118:121]
	v_mfma_f32_16x16x32_bf16 v[114:117], v[182:185], v[190:193], v[114:117]
	v_mfma_f32_16x16x32_bf16 v[102:105], v[174:177], v[200:203], v[102:105]
	v_mfma_f32_16x16x32_bf16 v[98:101], v[182:185], v[200:203], v[98:101]
	v_mfma_f32_16x16x32_bf16 v[86:89], v[174:177], v[208:211], v[86:89]
	v_mfma_f32_16x16x32_bf16 v[82:85], v[182:185], v[208:211], v[82:85]
	v_mfma_f32_16x16x32_bf16 v[70:73], v[174:177], v[216:219], v[70:73]
	v_mfma_f32_16x16x32_bf16 v[66:69], v[182:185], v[216:219], v[66:69]
	s_barrier
	s_add_i32 s36, s56, s33
	v_lshl_add_u64 v[146:147], v[146:147], 0, s[8:9]
	s_mov_b32 m0, s36
	ds_read_b128 v[186:189], v152 offset:49152
	ds_read_b128 v[190:193], v152 offset:50176
	ds_read_b128 v[194:197], v152 offset:51200
	ds_read_b128 v[200:203], v152 offset:52224
	ds_read_b128 v[204:207], v152 offset:53248
	ds_read_b128 v[208:211], v152 offset:54272
	ds_read_b128 v[212:215], v152 offset:55296
	ds_read_b128 v[216:219], v152 offset:56320
	global_load_lds_dwordx4 v[146:147], off
	s_add_i32 m0, s36, 0x2000
	s_add_u32 s34, s34, 0x100080
	v_lshl_add_u64 v[146:147], v[220:221], 0, s[8:9]
	s_addc_u32 s35, s35, 0
	s_add_i32 s36, s57, s33
	global_load_lds_dwordx4 v[146:147], off
	s_mov_b32 m0, s36
	s_nop 0
	global_load_lds_dwordx4 v134, s[34:35]
	s_add_i32 m0, s36, 0x2000
	s_nop 0
	global_load_lds_dwordx4 v130, s[34:35]
	v_lshl_add_u64 v[146:147], v[222:223], 0, s[8:9]
	s_mov_b32 m0, s44
	s_nop 0
	global_load_lds_dwordx4 v[146:147], off
	v_lshl_add_u64 v[146:147], v[224:225], 0, s[8:9]
	s_mov_b32 m0, s45
	s_nop 0
	global_load_lds_dwordx4 v[146:147], off
	s_waitcnt vmcnt(8)
	s_waitcnt lgkmcnt(0)
	s_barrier
	v_mfma_f32_16x16x32_bf16 v[62:65], v[154:157], v[186:189], v[62:65]
	v_mfma_f32_16x16x32_bf16 v[58:61], v[162:165], v[186:189], v[58:61]
	v_mfma_f32_16x16x32_bf16 v[46:49], v[154:157], v[194:197], v[46:49]
	v_mfma_f32_16x16x32_bf16 v[42:45], v[162:165], v[194:197], v[42:45]
	v_mfma_f32_16x16x32_bf16 v[30:33], v[154:157], v[204:207], v[30:33]
	v_mfma_f32_16x16x32_bf16 v[26:29], v[162:165], v[204:207], v[26:29]
	v_mfma_f32_16x16x32_bf16 v[14:17], v[154:157], v[212:215], v[14:17]
	v_mfma_f32_16x16x32_bf16 v[10:13], v[162:165], v[212:215], v[10:13]
	v_mfma_f32_16x16x32_bf16 v[62:65], v[158:161], v[190:193], v[62:65]
	v_mfma_f32_16x16x32_bf16 v[58:61], v[166:169], v[190:193], v[58:61]
	v_mfma_f32_16x16x32_bf16 v[46:49], v[158:161], v[200:203], v[46:49]
	v_mfma_f32_16x16x32_bf16 v[42:45], v[166:169], v[200:203], v[42:45]
	v_mfma_f32_16x16x32_bf16 v[30:33], v[158:161], v[208:211], v[30:33]
	v_mfma_f32_16x16x32_bf16 v[26:29], v[166:169], v[208:211], v[26:29]
	v_mfma_f32_16x16x32_bf16 v[14:17], v[158:161], v[216:219], v[14:17]
	v_mfma_f32_16x16x32_bf16 v[10:13], v[166:169], v[216:219], v[10:13]
	v_mfma_f32_16x16x32_bf16 v[54:57], v[170:173], v[186:189], v[54:57]
	v_mfma_f32_16x16x32_bf16 v[50:53], v[178:181], v[186:189], v[50:53]
	v_mfma_f32_16x16x32_bf16 v[38:41], v[170:173], v[194:197], v[38:41]
	v_mfma_f32_16x16x32_bf16 v[34:37], v[178:181], v[194:197], v[34:37]
	v_mfma_f32_16x16x32_bf16 v[22:25], v[170:173], v[204:207], v[22:25]
	v_mfma_f32_16x16x32_bf16 v[18:21], v[178:181], v[204:207], v[18:21]
	v_mfma_f32_16x16x32_bf16 v[6:9], v[170:173], v[212:215], v[6:9]
	v_mfma_f32_16x16x32_bf16 v[2:5], v[178:181], v[212:215], v[2:5]
	v_mfma_f32_16x16x32_bf16 v[54:57], v[174:177], v[190:193], v[54:57]
	v_mfma_f32_16x16x32_bf16 v[50:53], v[182:185], v[190:193], v[50:53]
	v_mfma_f32_16x16x32_bf16 v[38:41], v[174:177], v[200:203], v[38:41]
	v_mfma_f32_16x16x32_bf16 v[34:37], v[182:185], v[200:203], v[34:37]
	v_mfma_f32_16x16x32_bf16 v[22:25], v[174:177], v[208:211], v[22:25]
	v_mfma_f32_16x16x32_bf16 v[18:21], v[182:185], v[208:211], v[18:21]
	v_mfma_f32_16x16x32_bf16 v[6:9], v[174:177], v[216:219], v[6:9]
	v_mfma_f32_16x16x32_bf16 v[2:5], v[182:185], v[216:219], v[2:5]
	s_barrier
	s_add_i32 s55, s55, 2
	s_add_u32 s30, s30, 0x100
	s_addc_u32 s31, s31, 0
	s_add_u32 s53, s53, 0x100
	s_addc_u32 s54, s54, 0
	s_cmp_gt_u32 s55, 61
	s_cbranch_scc0 .LBB0_1081
	s_and_b64 vcc, exec, s[10:11]
	s_cbranch_vccz .LBB0_1084
	s_barrier

; #define PG8_STAGE(bufoff, gbase, voff) do { _Pragma("unroll") for (int _i = 0; _i < 2; ++_i) \
;         __builtin_amdgcn_global_load_lds((const unsigned*)((const char*)(gbase) + (voff)[_i]), (PG8_LAS unsigned*)(lds + (bufoff) + ldsw + _i * 8192), 16, 0, 0); } while (0)
; #define PG8_LDA(dst, b, h) do { _Pragma("unroll") for (int m = 0; m < 4; ++m) _Pragma("unroll") for (int k = 0; k < 2; ++k) dst[m][k] = *(const PG8_LAS bf16x8*)(lds + PG8_SA(b, h) + aoff + m * 2048 + k * 1024); } while (0)
; #define PG8_LDB(dst, b, h) do { _Pragma("unroll") for (int n = 0; n < 2; ++n) _Pragma("unroll") for (int k = 0; k < 2; ++k) dst[n][k] = *(const PG8_LAS bf16x8*)(lds + PG8_SB(b, h) + boff + n * 2048 + k * 1024); } while (0)
; #define PG8_MMA(ai, bj, At, Bt) do { __builtin_amdgcn_s_setprio(1); _Pragma("unroll") for (int m = 0; m < 4; ++m) _Pragma("unroll") for (int n = 0; n < 2; ++n) _Pragma("unroll") for (int k = 0; k < 2; ++k) \
;         acc[ai][bj][m][n] = __builtin_amdgcn_mfma_f32_16x16x32_bf16(Bt[n][k], At[m][k], acc[ai][bj][m][n], 0, 0, 0); __builtin_amdgcn_s_setprio(0); } while (0)
; #define PG8_WAIT_V(n) asm volatile("s_waitcnt vmcnt(" #n ")" ::: "memory")
; #define PG8_WAIT_L(n) asm volatile("s_waitcnt lgkmcnt(" #n ")" ::: "memory")
; #define PG8_BAR __builtin_amdgcn_s_barrier()
; #define PG8_SCHED __builtin_amdgcn_sched_barrier(0)
; template <class Epi, class Sched, bool ALIGN_EPI = false, bool SP2 = false>
; __device__ __forceinline__ void gemm_phase(PG8_LAS unsigned char* lds, const Gemm g, const Sched& S, const Epi& E) {
;     ...
;             PG8_LDB(B0, 0, 0); PG8_LDB(B1, 0, 1); PG8_SCHED; PG8_LDA(At, 0, 0); PG8_STAGE(PG8_SA(1, 1), a1 + hstep, voffA);
;             PG8_WAIT_V(8); PG8_WAIT_L(0); PG8_BAR; PG8_MMA(0, 0, At, B0); PG8_MMA(0, 1, At, B1); PG8_BAR; PG8_SCHED;
;             PG8_LDA(At, 0, 1); PG8_STAGE(PG8_SB(0, 0), b2, voffB); PG8_STAGE(PG8_SB(0, 1), b2 + hstep, voffB); PG8_STAGE(PG8_SA(0, 0), a2, voffA);
;             PG8_WAIT_V(8); PG8_WAIT_L(0); PG8_BAR; PG8_MMA(1, 0, At, B0); PG8_MMA(1, 1, At, B1); PG8_BAR; PG8_SCHED;
.LBB0_1164:
	ds_read_b128 v[140:143], v193
	ds_read_b128 v[144:147], v193 offset:1024
	ds_read_b128 v[148:151], v193 offset:2048
	ds_read_b128 v[152:155], v193 offset:3072
	ds_read_b128 v[156:159], v194
	ds_read_b128 v[160:163], v194 offset:1024
	ds_read_b128 v[164:167], v194 offset:2048
	ds_read_b128 v[168:171], v194 offset:3072
	s_add_u32 s16, s14, 0xffd50080
	s_addc_u32 s17, s15, -1
	s_cmpk_eq_i32 s41, 0xa8
	s_cselect_b32 s21, s5, s17
	s_cselect_b32 s20, s4, s16
	s_cselect_b32 s17, s13, s40
	s_cselect_b32 s16, s12, s39
	s_add_i32 m0, s24, 0xc000
	ds_read_b128 v[172:175], v195
	ds_read_b128 v[176:179], v195 offset:1024
	ds_read_b128 v[180:183], v195 offset:2048
	ds_read_b128 v[184:187], v195 offset:3072
	ds_read_b128 v[196:199], v195 offset:4096
	ds_read_b128 v[200:203], v195 offset:5120
	ds_read_b128 v[204:207], v195 offset:6144
	ds_read_b128 v[208:211], v195 offset:7168
	global_load_lds_dwordx4 v132, s[14:15]
	s_add_i32 m0, s24, 0xe000
	s_nop 0
	global_load_lds_dwordx4 v134, s[14:15]
	s_waitcnt vmcnt(8)
	s_waitcnt lgkmcnt(0)
	s_barrier
	v_mfma_f32_16x16x32_bf16 v[124:127], v[140:143], v[172:175], v[124:127]
	v_mfma_f32_16x16x32_bf16 v[120:123], v[148:151], v[172:175], v[120:123]
	v_mfma_f32_16x16x32_bf16 v[112:115], v[140:143], v[180:183], v[112:115]
	v_mfma_f32_16x16x32_bf16 v[104:107], v[148:151], v[180:183], v[104:107]
	v_mfma_f32_16x16x32_bf16 v[96:99], v[140:143], v[196:199], v[96:99]
	v_mfma_f32_16x16x32_bf16 v[88:91], v[148:151], v[196:199], v[88:91]
	v_mfma_f32_16x16x32_bf16 v[80:83], v[140:143], v[204:207], v[80:83]
	v_mfma_f32_16x16x32_bf16 v[72:75], v[148:151], v[204:207], v[72:75]
	v_mfma_f32_16x16x32_bf16 v[124:127], v[144:147], v[176:179], v[124:127]
	v_mfma_f32_16x16x32_bf16 v[120:123], v[152:155], v[176:179], v[120:123]
	v_mfma_f32_16x16x32_bf16 v[112:115], v[144:147], v[184:187], v[112:115]
	v_mfma_f32_16x16x32_bf16 v[104:107], v[152:155], v[184:187], v[104:107]
	v_mfma_f32_16x16x32_bf16 v[96:99], v[144:147], v[200:203], v[96:99]
	v_mfma_f32_16x16x32_bf16 v[88:91], v[152:155], v[200:203], v[88:91]
	v_mfma_f32_16x16x32_bf16 v[80:83], v[144:147], v[208:211], v[80:83]
	v_mfma_f32_16x16x32_bf16 v[72:75], v[152:155], v[208:211], v[72:75]
	v_mfma_f32_16x16x32_bf16 v[116:119], v[156:159], v[172:175], v[116:119]
	v_mfma_f32_16x16x32_bf16 v[108:111], v[164:167], v[172:175], v[108:111]
	v_mfma_f32_16x16x32_bf16 v[100:103], v[156:159], v[180:183], v[100:103]
	v_mfma_f32_16x16x32_bf16 v[92:95], v[164:167], v[180:183], v[92:95]
	v_mfma_f32_16x16x32_bf16 v[84:87], v[156:159], v[196:199], v[84:87]
	v_mfma_f32_16x16x32_bf16 v[76:79], v[164:167], v[196:199], v[76:79]
	v_mfma_f32_16x16x32_bf16 v[68:71], v[156:159], v[204:207], v[68:71]
	v_mfma_f32_16x16x32_bf16 v[64:67], v[164:167], v[204:207], v[64:67]
	v_mfma_f32_16x16x32_bf16 v[116:119], v[160:163], v[176:179], v[116:119]
	v_mfma_f32_16x16x32_bf16 v[108:111], v[168:171], v[176:179], v[108:111]
	v_mfma_f32_16x16x32_bf16 v[100:103], v[160:163], v[184:187], v[100:103]
	v_mfma_f32_16x16x32_bf16 v[92:95], v[168:171], v[184:187], v[92:95]
	v_mfma_f32_16x16x32_bf16 v[84:87], v[160:163], v[200:203], v[84:87]
	v_mfma_f32_16x16x32_bf16 v[76:79], v[168:171], v[200:203], v[76:79]
	v_mfma_f32_16x16x32_bf16 v[68:71], v[160:163], v[208:211], v[68:71]
	v_mfma_f32_16x16x32_bf16 v[64:67], v[168:171], v[208:211], v[64:67]
	s_barrier
	s_add_i32 s42, s33, s23
	v_lshl_add_u64 v[188:189], s[16:17], 0, v[128:129]
	s_mov_b32 m0, s42
	ds_read_b128 v[172:175], v195 offset:16384
	ds_read_b128 v[176:179], v195 offset:17408
	ds_read_b128 v[180:183], v195 offset:18432
	ds_read_b128 v[184:187], v195 offset:19456
	ds_read_b128 v[196:199], v195 offset:20480
	ds_read_b128 v[200:203], v195 offset:21504
	ds_read_b128 v[204:207], v195 offset:22528
	ds_read_b128 v[208:211], v195 offset:23552
	global_load_lds_dwordx4 v128, s[16:17]
	s_add_i32 m0, s42, 0x2000
	s_add_u32 s42, s16, 0x2b0000
	v_lshl_add_u64 v[212:213], s[16:17], 0, v[130:131]
	s_addc_u32 s43, s17, 0
	s_add_i32 s44, s34, s23
	global_load_lds_dwordx4 v130, s[16:17]
	s_mov_b32 m0, s44
	v_lshl_add_u64 v[216:217], s[20:21], 0, v[130:131]
	global_load_lds_dwordx4 v128, s[42:43]
	s_add_i32 m0, s44, 0x2000
	s_nop 0
	global_load_lds_dwordx4 v130, s[42:43]
	v_lshl_add_u64 v[214:215], s[20:21], 0, v[128:129]
	s_mov_b32 m0, s24
	s_nop 0
	global_load_lds_dwordx4 v128, s[20:21]
	s_mov_b32 m0, s25
	s_nop 0
	global_load_lds_dwordx4 v130, s[20:21]
	s_waitcnt vmcnt(8)
	s_waitcnt lgkmcnt(0)
	s_barrier
	v_mfma_f32_16x16x32_bf16 v[60:63], v[140:143], v[172:175], v[60:63]
	v_mfma_f32_16x16x32_bf16 v[56:59], v[148:151], v[172:175], v[56:59]
	v_mfma_f32_16x16x32_bf16 v[48:51], v[140:143], v[180:183], v[48:51]
	v_mfma_f32_16x16x32_bf16 v[40:43], v[148:151], v[180:183], v[40:43]
	v_mfma_f32_16x16x32_bf16 v[32:35], v[140:143], v[196:199], v[32:35]
	v_mfma_f32_16x16x32_bf16 v[24:27], v[148:151], v[196:199], v[24:27]
	v_mfma_f32_16x16x32_bf16 v[16:19], v[140:143], v[204:207], v[16:19]
	v_mfma_f32_16x16x32_bf16 v[8:11], v[148:151], v[204:207], v[8:11]
	v_mfma_f32_16x16x32_bf16 v[60:63], v[144:147], v[176:179], v[60:63]
	v_mfma_f32_16x16x32_bf16 v[56:59], v[152:155], v[176:179], v[56:59]
	v_mfma_f32_16x16x32_bf16 v[48:51], v[144:147], v[184:187], v[48:51]
	v_mfma_f32_16x16x32_bf16 v[40:43], v[152:155], v[184:187], v[40:43]
	v_mfma_f32_16x16x32_bf16 v[32:35], v[144:147], v[200:203], v[32:35]
	v_mfma_f32_16x16x32_bf16 v[24:27], v[152:155], v[200:203], v[24:27]
	v_mfma_f32_16x16x32_bf16 v[16:19], v[144:147], v[208:211], v[16:19]
	v_mfma_f32_16x16x32_bf16 v[8:11], v[152:155], v[208:211], v[8:11]
	v_mfma_f32_16x16x32_bf16 v[52:55], v[156:159], v[172:175], v[52:55]
	v_mfma_f32_16x16x32_bf16 v[44:47], v[164:167], v[172:175], v[44:47]
	v_mfma_f32_16x16x32_bf16 v[36:39], v[156:159], v[180:183], v[36:39]
	v_mfma_f32_16x16x32_bf16 v[28:31], v[164:167], v[180:183], v[28:31]
	v_mfma_f32_16x16x32_bf16 v[20:23], v[156:159], v[196:199], v[20:23]
	v_mfma_f32_16x16x32_bf16 v[12:15], v[164:167], v[196:199], v[12:15]
	v_mfma_f32_16x16x32_bf16 v[4:7], v[156:159], v[204:207], v[4:7]
	v_mfma_f32_16x16x32_bf16 v[0:3], v[164:167], v[204:207], v[0:3]
	v_mfma_f32_16x16x32_bf16 v[52:55], v[160:163], v[176:179], v[52:55]
	v_mfma_f32_16x16x32_bf16 v[44:47], v[168:171], v[176:179], v[44:47]
	v_mfma_f32_16x16x32_bf16 v[36:39], v[160:163], v[184:187], v[36:39]
	v_mfma_f32_16x16x32_bf16 v[28:31], v[168:171], v[184:187], v[28:31]
	v_mfma_f32_16x16x32_bf16 v[20:23], v[160:163], v[200:203], v[20:23]
	v_mfma_f32_16x16x32_bf16 v[12:15], v[168:171], v[200:203], v[12:15]
	v_mfma_f32_16x16x32_bf16 v[4:7], v[160:163], v[208:211], v[4:7]
	v_mfma_f32_16x16x32_bf16 v[0:3], v[168:171], v[208:211], v[0:3]
	s_barrier
; #define PG8_STAGE(bufoff, gbase, voff) do { _Pragma("unroll") for (int _i = 0; _i < 2; ++_i) \
;         __builtin_amdgcn_global_load_lds((const unsigned*)((const char*)(gbase) + (voff)[_i]), (PG8_LAS unsigned*)(lds + (bufoff) + ldsw + _i * 8192), 16, 0, 0); } while (0)
; #define PG8_LDA(dst, b, h) do { _Pragma("unroll") for (int m = 0; m < 4; ++m) _Pragma("unroll") for (int k = 0; k < 2; ++k) dst[m][k] = *(const PG8_LAS bf16x8*)(lds + PG8_SA(b, h) + aoff + m * 2048 + k * 1024); } while (0)
; #define PG8_LDB(dst, b, h) do { _Pragma("unroll") for (int n = 0; n < 2; ++n) _Pragma("unroll") for (int k = 0; k < 2; ++k) dst[n][k] = *(const PG8_LAS bf16x8*)(lds + PG8_SB(b, h) + boff + n * 2048 + k * 1024); } while (0)
; #define PG8_MMA(ai, bj, At, Bt) do { __builtin_amdgcn_s_setprio(1); _Pragma("unroll") for (int m = 0; m < 4; ++m) _Pragma("unroll") for (int n = 0; n < 2; ++n) _Pragma("unroll") for (int k = 0; k < 2; ++k) \
;         acc[ai][bj][m][n] = __builtin_amdgcn_mfma_f32_16x16x32_bf16(Bt[n][k], At[m][k], acc[ai][bj][m][n], 0, 0, 0); __builtin_amdgcn_s_setprio(0); } while (0)
; #define PG8_WAIT_V(n) asm volatile("s_waitcnt vmcnt(" #n ")" ::: "memory")
; #define PG8_WAIT_L(n) asm volatile("s_waitcnt lgkmcnt(" #n ")" ::: "memory")
; #define PG8_BAR __builtin_amdgcn_s_barrier()
; #define PG8_SCHED __builtin_amdgcn_sched_barrier(0)
; template <class Epi, class Sched, bool ALIGN_EPI = false, bool SP2 = false>
; __device__ __forceinline__ void gemm_phase(PG8_LAS unsigned char* lds, const Gemm g, const Sched& S, const Epi& E) {
;     ...
;         for (int t = 0; t < nt; t += 2) {
;             const bool last = (t == nt - 2);
;             const char* a1 = cA + (size_t)(t + 1) * kstep;
;             const char* a2 = last ? nA : cA + (size_t)(t + 2) * kstep; const char* b2 = last ? nB : cB + (size_t)(t + 2) * kstep;
;     ...
;             PG8_LDB(B0, 1, 0); PG8_LDB(B1, 1, 1); PG8_SCHED; PG8_LDA(At, 1, 0); PG8_STAGE(PG8_SA(0, 1), a2 + hstep, voffA);
;             PG8_WAIT_V(8); PG8_WAIT_L(0); PG8_BAR; PG8_MMA(0, 0, At, B0); PG8_MMA(0, 1, At, B1); PG8_BAR; PG8_SCHED;
;             PG8_LDA(At, 1, 1); PG8_STAGE(PG8_SB(1, 0), b3, voffB); PG8_STAGE(PG8_SB(1, 1), b3 + hstep, voffB); PG8_STAGE(PG8_SA(1, 0), a3, voffA);
;             PG8_WAIT_V(8); PG8_WAIT_L(0); PG8_BAR; PG8_MMA(1, 0, At, B0); PG8_MMA(1, 1, At, B1); PG8_BAR; PG8_SCHED;
	s_add_i32 s42, 0, 0x18000
	s_add_i32 s43, 0, 0x1c000
	v_add_u32_e32 v152, s42, v191
	v_add_u32_e32 v168, s43, v191
	ds_read_b128 v[140:143], v152
	ds_read_b128 v[144:147], v152 offset:1024
	ds_read_b128 v[148:151], v152 offset:2048
	ds_read_b128 v[152:155], v152 offset:3072
	ds_read_b128 v[156:159], v168
	ds_read_b128 v[160:163], v168 offset:1024
	ds_read_b128 v[164:167], v168 offset:2048
	ds_read_b128 v[168:171], v168 offset:3072
	s_add_u32 s20, s20, 0x2b0000
	s_addc_u32 s21, s21, 0
	s_mov_b32 m0, s26
	ds_read_b128 v[172:175], v195 offset:32768
	ds_read_b128 v[176:179], v195 offset:33792
	ds_read_b128 v[180:183], v195 offset:34816
	ds_read_b128 v[184:187], v195 offset:35840
	ds_read_b128 v[196:199], v195 offset:36864
	ds_read_b128 v[200:203], v195 offset:37888
	ds_read_b128 v[204:207], v195 offset:38912
	ds_read_b128 v[208:211], v195 offset:39936
	global_load_lds_dwordx4 v128, s[20:21]
	s_mov_b32 m0, s27
	s_nop 0
	global_load_lds_dwordx4 v130, s[20:21]
	s_waitcnt vmcnt(8)
	s_waitcnt lgkmcnt(0)
	s_barrier
	v_mfma_f32_16x16x32_bf16 v[124:127], v[140:143], v[172:175], v[124:127]
	v_mfma_f32_16x16x32_bf16 v[120:123], v[148:151], v[172:175], v[120:123]
	v_mfma_f32_16x16x32_bf16 v[112:115], v[140:143], v[180:183], v[112:115]
	v_mfma_f32_16x16x32_bf16 v[104:107], v[148:151], v[180:183], v[104:107]
	v_mfma_f32_16x16x32_bf16 v[96:99], v[140:143], v[196:199], v[96:99]
	v_mfma_f32_16x16x32_bf16 v[88:91], v[148:151], v[196:199], v[88:91]
	v_mfma_f32_16x16x32_bf16 v[80:83], v[140:143], v[204:207], v[80:83]
	v_mfma_f32_16x16x32_bf16 v[72:75], v[148:151], v[204:207], v[72:75]
	v_mfma_f32_16x16x32_bf16 v[124:127], v[144:147], v[176:179], v[124:127]
	v_mfma_f32_16x16x32_bf16 v[120:123], v[152:155], v[176:179], v[120:123]
	v_mfma_f32_16x16x32_bf16 v[112:115], v[144:147], v[184:187], v[112:115]
	v_mfma_f32_16x16x32_bf16 v[104:107], v[152:155], v[184:187], v[104:107]
	v_mfma_f32_16x16x32_bf16 v[96:99], v[144:147], v[200:203], v[96:99]
	v_mfma_f32_16x16x32_bf16 v[88:91], v[152:155], v[200:203], v[88:91]
	v_mfma_f32_16x16x32_bf16 v[80:83], v[144:147], v[208:211], v[80:83]
	v_mfma_f32_16x16x32_bf16 v[72:75], v[152:155], v[208:211], v[72:75]
	v_mfma_f32_16x16x32_bf16 v[116:119], v[156:159], v[172:175], v[116:119]
	v_mfma_f32_16x16x32_bf16 v[108:111], v[164:167], v[172:175], v[108:111]
	v_mfma_f32_16x16x32_bf16 v[100:103], v[156:159], v[180:183], v[100:103]
	v_mfma_f32_16x16x32_bf16 v[92:95], v[164:167], v[180:183], v[92:95]
	v_mfma_f32_16x16x32_bf16 v[84:87], v[156:159], v[196:199], v[84:87]
	v_mfma_f32_16x16x32_bf16 v[76:79], v[164:167], v[196:199], v[76:79]
	v_mfma_f32_16x16x32_bf16 v[68:71], v[156:159], v[204:207], v[68:71]
	v_mfma_f32_16x16x32_bf16 v[64:67], v[164:167], v[204:207], v[64:67]
	v_mfma_f32_16x16x32_bf16 v[116:119], v[160:163], v[176:179], v[116:119]
	v_mfma_f32_16x16x32_bf16 v[108:111], v[168:171], v[176:179], v[108:111]
	v_mfma_f32_16x16x32_bf16 v[100:103], v[160:163], v[184:187], v[100:103]
	v_mfma_f32_16x16x32_bf16 v[92:95], v[168:171], v[184:187], v[92:95]
	v_mfma_f32_16x16x32_bf16 v[84:87], v[160:163], v[200:203], v[84:87]
	v_mfma_f32_16x16x32_bf16 v[76:79], v[168:171], v[200:203], v[76:79]
	v_mfma_f32_16x16x32_bf16 v[68:71], v[160:163], v[208:211], v[68:71]
	v_mfma_f32_16x16x32_bf16 v[64:67], v[168:171], v[208:211], v[64:67]
	s_barrier
	s_add_i32 s20, s42, s23
	v_lshl_add_u64 v[188:189], v[188:189], 0, s[8:9]
	s_mov_b32 m0, s20
	ds_read_b128 v[172:175], v195 offset:49152
	ds_read_b128 v[176:179], v195 offset:50176
	ds_read_b128 v[180:183], v195 offset:51200
	ds_read_b128 v[184:187], v195 offset:52224
	ds_read_b128 v[196:199], v195 offset:53248
	ds_read_b128 v[200:203], v195 offset:54272
	ds_read_b128 v[204:207], v195 offset:55296
	ds_read_b128 v[208:211], v195 offset:56320
	global_load_lds_dwordx4 v[188:189], off
	s_add_i32 m0, s20, 0x2000
	s_add_u32 s16, s16, 0x2b0080
	v_lshl_add_u64 v[188:189], v[212:213], 0, s[8:9]
	s_addc_u32 s17, s17, 0
	s_add_i32 s20, s43, s23
	global_load_lds_dwordx4 v[188:189], off
	s_mov_b32 m0, s20
	s_nop 0
	global_load_lds_dwordx4 v128, s[16:17]
	s_add_i32 m0, s20, 0x2000
	s_nop 0
	global_load_lds_dwordx4 v130, s[16:17]
	v_lshl_add_u64 v[188:189], v[214:215], 0, s[8:9]
	s_mov_b32 m0, s29
	s_nop 0
	global_load_lds_dwordx4 v[188:189], off
	v_lshl_add_u64 v[188:189], v[216:217], 0, s[8:9]
	s_mov_b32 m0, s30
	s_nop 0
	global_load_lds_dwordx4 v[188:189], off
	s_waitcnt vmcnt(8)
	s_waitcnt lgkmcnt(0)
	s_barrier
	v_mfma_f32_16x16x32_bf16 v[60:63], v[140:143], v[172:175], v[60:63]
	v_mfma_f32_16x16x32_bf16 v[56:59], v[148:151], v[172:175], v[56:59]
	v_mfma_f32_16x16x32_bf16 v[48:51], v[140:143], v[180:183], v[48:51]
	v_mfma_f32_16x16x32_bf16 v[40:43], v[148:151], v[180:183], v[40:43]
	v_mfma_f32_16x16x32_bf16 v[32:35], v[140:143], v[196:199], v[32:35]
	v_mfma_f32_16x16x32_bf16 v[24:27], v[148:151], v[196:199], v[24:27]
	v_mfma_f32_16x16x32_bf16 v[16:19], v[140:143], v[204:207], v[16:19]
	v_mfma_f32_16x16x32_bf16 v[8:11], v[148:151], v[204:207], v[8:11]
	v_mfma_f32_16x16x32_bf16 v[60:63], v[144:147], v[176:179], v[60:63]
	v_mfma_f32_16x16x32_bf16 v[56:59], v[152:155], v[176:179], v[56:59]
	v_mfma_f32_16x16x32_bf16 v[48:51], v[144:147], v[184:187], v[48:51]
	v_mfma_f32_16x16x32_bf16 v[40:43], v[152:155], v[184:187], v[40:43]
	v_mfma_f32_16x16x32_bf16 v[32:35], v[144:147], v[200:203], v[32:35]
	v_mfma_f32_16x16x32_bf16 v[24:27], v[152:155], v[200:203], v[24:27]
	v_mfma_f32_16x16x32_bf16 v[16:19], v[144:147], v[208:211], v[16:19]
	v_mfma_f32_16x16x32_bf16 v[8:11], v[152:155], v[208:211], v[8:11]
	v_mfma_f32_16x16x32_bf16 v[52:55], v[156:159], v[172:175], v[52:55]
	v_mfma_f32_16x16x32_bf16 v[44:47], v[164:167], v[172:175], v[44:47]
	v_mfma_f32_16x16x32_bf16 v[36:39], v[156:159], v[180:183], v[36:39]
	v_mfma_f32_16x16x32_bf16 v[28:31], v[164:167], v[180:183], v[28:31]
	v_mfma_f32_16x16x32_bf16 v[20:23], v[156:159], v[196:199], v[20:23]
	v_mfma_f32_16x16x32_bf16 v[12:15], v[164:167], v[196:199], v[12:15]
	v_mfma_f32_16x16x32_bf16 v[4:7], v[156:159], v[204:207], v[4:7]
	v_mfma_f32_16x16x32_bf16 v[0:3], v[164:167], v[204:207], v[0:3]
	v_mfma_f32_16x16x32_bf16 v[52:55], v[160:163], v[176:179], v[52:55]
	v_mfma_f32_16x16x32_bf16 v[44:47], v[168:171], v[176:179], v[44:47]
	v_mfma_f32_16x16x32_bf16 v[36:39], v[160:163], v[184:187], v[36:39]
	v_mfma_f32_16x16x32_bf16 v[28:31], v[168:171], v[184:187], v[28:31]
	v_mfma_f32_16x16x32_bf16 v[20:23], v[160:163], v[200:203], v[20:23]
	v_mfma_f32_16x16x32_bf16 v[12:15], v[168:171], v[200:203], v[12:15]
	v_mfma_f32_16x16x32_bf16 v[4:7], v[160:163], v[208:211], v[4:7]
	v_mfma_f32_16x16x32_bf16 v[0:3], v[168:171], v[208:211], v[0:3]
	s_barrier
	s_add_i32 s41, s41, 2
	s_add_u32 s14, s14, 0x100
	s_addc_u32 s15, s15, 0
	s_add_u32 s39, s39, 0x100
	s_addc_u32 s40, s40, 0
	s_cmpk_gt_u32 s41, 0xa9
	s_cbranch_scc0 .LBB0_1164
	s_and_b64 vcc, exec, s[10:11]
	s_cbranch_vccz .LBB0_1167
	s_barrier
